# prologue pooling-weight fold rewritten (lane-distributed w_pool/scale loads + readlane broadcast, 5-deep row load pipeline), 2 fold waves + 6 stream waves; on top of v27
# speedup vs baseline: 1.0011x; 1.0011x over previous
; __device__ __forceinline__ void prologue(const Params& p, LAS unsigned char* lds) {
;     ...
;         const int gwv = blockIdx.x * 8 + wid, NGWV = gridDim.x * 8;
;         for (int it = gwv; it < 2 * 1024; it += NGWV) {
;             const int l = it >> 10, r = it & 1023, nblk = r & 15, kg = r >> 4, g = kg >> 4, c0 = (kg & 15) * 8, n = nblk * 64 + lane;
;             const float* wp = p.w_pool + ((size_t)l * 4 + g) * 128 * 128 + (size_t)c0 * 128;
;             const float* sc = p.pool_scale + l * 512 + g * 128;
;             const float* wb = p.w_br_pool + (size_t)l * 512 * DM + (size_t)(g * 128) * DM + n;
.LBB0_46:
	s_or_b64 exec, exec, s[10:11]
	s_load_dwordx16 s[52:67], s[0:1], 0x0
	s_lshl_b32 s6, s92, 3
	v_and_b32_e32 v39, 63, v222
	v_mov_b32_e32 v1, 0
	s_waitcnt lgkmcnt(0)
	v_writelane_b32 v249, s52, 4
	s_nop 1
	v_writelane_b32 v249, s53, 5
	v_writelane_b32 v249, s54, 6
	v_writelane_b32 v249, s55, 7
	v_writelane_b32 v249, s56, 8
	v_writelane_b32 v249, s57, 9
	v_writelane_b32 v249, s58, 10
	v_writelane_b32 v249, s59, 11
	v_writelane_b32 v249, s60, 12
	v_writelane_b32 v249, s61, 13
	v_writelane_b32 v249, s62, 14
	v_writelane_b32 v249, s63, 15
	v_writelane_b32 v249, s64, 16
	v_writelane_b32 v249, s65, 17
	v_writelane_b32 v249, s66, 18
	v_writelane_b32 v249, s67, 19
	s_load_dwordx16 s[52:67], s[0:1], 0x40
	s_lshl_b32 s0, s81, 3
	s_lshr_b32 s1, s17, 6
	s_add_i32 s0, s1, s0
	s_cmpk_gt_i32 s0, 0x7ff
	s_waitcnt lgkmcnt(0)
	v_writelane_b32 v249, s52, 20
	s_nop 1
	v_writelane_b32 v249, s53, 21
	v_writelane_b32 v249, s54, 22
	v_writelane_b32 v249, s55, 23
	v_writelane_b32 v249, s56, 24
	v_writelane_b32 v249, s57, 25
	v_writelane_b32 v249, s58, 26
	v_writelane_b32 v249, s59, 27
	v_writelane_b32 v249, s60, 28
	v_writelane_b32 v249, s61, 29
	v_writelane_b32 v249, s62, 30
	v_writelane_b32 v249, s63, 31
	v_writelane_b32 v249, s64, 32
	v_writelane_b32 v249, s65, 33
	v_writelane_b32 v249, s66, 34
	v_writelane_b32 v249, s67, 35
	s_cbranch_scc1 .LBB0_51
	s_lshr_b32 s32, s17, 6
	s_cmp_lt_u32 s32, 6
	s_cbranch_scc1 .LBB0_51
	s_lshl_b32 s1, s1, 6
	v_readlane_b32 s52, v249, 20
	s_add_i32 s1, s16, s1
	v_readlane_b32 s58, v249, 26
	v_readlane_b32 s59, v249, 27
	s_add_u32 s9, s58, 28
	s_addc_u32 s18, s59, 0
	s_mov_b32 s5, 0
	s_movk_i32 s19, 0x2000
	s_movk_i32 s20, 0x4000
	s_movk_i32 s21, 0x6000
	s_movk_i32 s23, 0x7000
	s_mov_b32 s24, s0
	s_lshr_b32 s32, s17, 6
	s_add_i32 s32, s32, -6
	s_mul_i32 s24, s81, 2
	s_add_i32 s24, s24, s32
	s_lshl_b32 s1, s24, 6
	s_mul_i32 s32, s92, 2
	s_lshl_b32 s33, s32, 6
	v_readlane_b32 s53, v249, 21
	v_readlane_b32 s54, v249, 22
	v_readlane_b32 s55, v249, 23
	v_readlane_b32 s56, v249, 24
	v_readlane_b32 s57, v249, 25
	v_readlane_b32 s60, v249, 28
	v_readlane_b32 s61, v249, 29
	v_readlane_b32 s62, v249, 30
	v_readlane_b32 s63, v249, 31
	v_readlane_b32 s64, v249, 32
	v_readlane_b32 s65, v249, 33
	v_readlane_b32 s66, v249, 34
	v_readlane_b32 s67, v249, 35

; __device__ __forceinline__ void prologue(const Params& p, LAS unsigned char* lds) {
;     ...
;             const int l = it >> 10, r = it & 1023, nblk = r & 15, kg = r >> 4, g = kg >> 4, c0 = (kg & 15) * 8, n = nblk * 64 + lane;
;             const float* wp = p.w_pool + ((size_t)l * 4 + g) * 128 * 128 + (size_t)c0 * 128;
;             const float* sc = p.pool_scale + l * 512 + g * 128;
;             const float* wb = p.w_br_pool + (size_t)l * 512 * DM + (size_t)(g * 128) * DM + n;
;             float a[8];
; #pragma unroll
;             for (int i = 0; i < 8; ++i) a[i] = 0.f;
; #pragma unroll 8
;             for (int d = 0; d < 128; ++d) { const float x = wb[(size_t)d * DM] * sc[d];
; #pragma unroll
;                 for (int i = 0; i < 8; ++i) a[i] += wp[i * 128 + d] * x; }
.LBB0_49:
	v_lshlrev_b32_e32 v78, 2, v39
	s_add_u32 s70, s11, -28
	s_addc_u32 s71, s25, -1
	s_mov_b32 s68, 0x1000
	s_mov_b32 s69, 0
	global_load_dword v76, v78, s[26:27]
	global_load_dword v77, v78, s[26:27] offset:256
	global_load_dword v60, v78, s[70:71] offset:0
	global_load_dword v61, v78, s[70:71] offset:256
	global_load_dword v62, v78, s[70:71] offset:512
	global_load_dword v63, v78, s[70:71] offset:768
	global_load_dword v64, v78, s[70:71] offset:1024
	global_load_dword v65, v78, s[70:71] offset:1280
	global_load_dword v66, v78, s[70:71] offset:1536
	global_load_dword v67, v78, s[70:71] offset:1792
	global_load_dword v68, v78, s[70:71] offset:2048
	global_load_dword v69, v78, s[70:71] offset:2304
	global_load_dword v70, v78, s[70:71] offset:2560
	global_load_dword v71, v78, s[70:71] offset:2816
	global_load_dword v72, v78, s[70:71] offset:3072
	global_load_dword v73, v78, s[70:71] offset:3328
	global_load_dword v74, v78, s[70:71] offset:3584
	global_load_dword v75, v78, s[70:71] offset:3840
	v_lshl_add_u64 v[80:81], v[2:3], 0, s[68:69]
	s_mov_b32 s68, 0x2000
	global_load_dword v92, v[80:81], off offset:-4096
	global_load_dword v93, v[80:81], off
	v_lshl_add_u64 v[80:81], v[80:81], 0, s[68:69]
	global_load_dword v94, v[80:81], off offset:-4096
	global_load_dword v95, v[80:81], off
	v_lshl_add_u64 v[80:81], v[80:81], 0, s[68:69]
	global_load_dword v96, v[80:81], off offset:-4096
	global_load_dword v97, v[80:81], off
	v_lshl_add_u64 v[80:81], v[80:81], 0, s[68:69]
	global_load_dword v98, v[80:81], off offset:-4096
	global_load_dword v99, v[80:81], off
	v_lshl_add_u64 v[80:81], v[80:81], 0, s[68:69]
	global_load_dword v100, v[80:81], off offset:-4096
	global_load_dword v101, v[80:81], off
	v_lshl_add_u64 v[80:81], v[80:81], 0, s[68:69]
	global_load_dword v102, v[80:81], off offset:-4096
	global_load_dword v103, v[80:81], off
	v_lshl_add_u64 v[80:81], v[80:81], 0, s[68:69]
	global_load_dword v104, v[80:81], off offset:-4096
	global_load_dword v105, v[80:81], off
	v_lshl_add_u64 v[80:81], v[80:81], 0, s[68:69]
	global_load_dword v106, v[80:81], off offset:-4096
	global_load_dword v107, v[80:81], off
	v_lshl_add_u64 v[80:81], v[80:81], 0, s[68:69]
	global_load_dword v108, v[80:81], off offset:-4096
	global_load_dword v109, v[80:81], off
	v_lshl_add_u64 v[80:81], v[80:81], 0, s[68:69]
	global_load_dword v110, v[80:81], off offset:-4096
	global_load_dword v111, v[80:81], off
	v_lshl_add_u64 v[80:81], v[80:81], 0, s[68:69]
	global_load_dword v112, v[80:81], off offset:-4096
	global_load_dword v113, v[80:81], off
	v_lshl_add_u64 v[80:81], v[80:81], 0, s[68:69]
	global_load_dword v114, v[80:81], off offset:-4096
	global_load_dword v115, v[80:81], off
	v_lshl_add_u64 v[80:81], v[80:81], 0, s[68:69]
	global_load_dword v116, v[80:81], off offset:-4096
	global_load_dword v117, v[80:81], off
	v_lshl_add_u64 v[80:81], v[80:81], 0, s[68:69]
	global_load_dword v118, v[80:81], off offset:-4096
	global_load_dword v119, v[80:81], off
	v_lshl_add_u64 v[80:81], v[80:81], 0, s[68:69]
	global_load_dword v120, v[80:81], off offset:-4096
	global_load_dword v121, v[80:81], off
	v_lshl_add_u64 v[80:81], v[80:81], 0, s[68:69]
	global_load_dword v122, v[80:81], off offset:-4096
	global_load_dword v123, v[80:81], off
	v_lshl_add_u64 v[80:81], v[80:81], 0, s[68:69]
	global_load_dword v124, v[80:81], off offset:-4096
	global_load_dword v125, v[80:81], off
	v_lshl_add_u64 v[80:81], v[80:81], 0, s[68:69]
	global_load_dword v126, v[80:81], off offset:-4096
	global_load_dword v127, v[80:81], off
	v_lshl_add_u64 v[80:81], v[80:81], 0, s[68:69]
	global_load_dword v128, v[80:81], off offset:-4096
	global_load_dword v129, v[80:81], off
	v_lshl_add_u64 v[80:81], v[80:81], 0, s[68:69]
	global_load_dword v130, v[80:81], off offset:-4096
	global_load_dword v131, v[80:81], off
	v_lshl_add_u64 v[80:81], v[80:81], 0, s[68:69]
	s_waitcnt vmcnt(32)
	v_readlane_b32 s72, v76, 0
	v_readlane_b32 s73, v60, 0
	v_readlane_b32 s74, v62, 0
	v_readlane_b32 s75, v64, 0
	v_readlane_b32 s76, v66, 0
	v_readlane_b32 s77, v68, 0
	v_readlane_b32 s78, v70, 0
	v_readlane_b32 s79, v72, 0
	v_readlane_b32 s80, v74, 0
	v_mul_f32_e32 v82, s72, v92
	v_fmac_f32_e32 v10, s73, v82
	v_fmac_f32_e32 v11, s74, v82
	v_fmac_f32_e32 v8, s75, v82
	v_fmac_f32_e32 v9, s76, v82
	v_fmac_f32_e32 v6, s77, v82
	v_fmac_f32_e32 v7, s78, v82
	v_fmac_f32_e32 v4, s79, v82
	v_fmac_f32_e32 v5, s80, v82
	v_readlane_b32 s82, v76, 1
	v_readlane_b32 s83, v60, 1
	v_readlane_b32 s84, v62, 1
	v_readlane_b32 s85, v64, 1
	v_readlane_b32 s86, v66, 1
	v_readlane_b32 s87, v68, 1
	v_readlane_b32 s88, v70, 1
	v_readlane_b32 s89, v72, 1
	v_readlane_b32 s90, v74, 1
	v_mul_f32_e32 v83, s82, v93
	v_fmac_f32_e32 v10, s83, v83
	v_fmac_f32_e32 v11, s84, v83
	v_fmac_f32_e32 v8, s85, v83
	v_fmac_f32_e32 v9, s86, v83
	v_fmac_f32_e32 v6, s87, v83
	v_fmac_f32_e32 v7, s88, v83
	v_fmac_f32_e32 v4, s89, v83
	v_fmac_f32_e32 v5, s90, v83
	v_readlane_b32 s72, v76, 2
	v_readlane_b32 s73, v60, 2
	v_readlane_b32 s74, v62, 2
	v_readlane_b32 s75, v64, 2
	v_readlane_b32 s76, v66, 2
	v_readlane_b32 s77, v68, 2
	v_readlane_b32 s78, v70, 2
	v_readlane_b32 s79, v72, 2
	v_readlane_b32 s80, v74, 2
	v_mul_f32_e32 v82, s72, v94
	v_fmac_f32_e32 v10, s73, v82
	v_fmac_f32_e32 v11, s74, v82
	v_fmac_f32_e32 v8, s75, v82
	v_fmac_f32_e32 v9, s76, v82
	v_fmac_f32_e32 v6, s77, v82
	v_fmac_f32_e32 v7, s78, v82
	v_fmac_f32_e32 v4, s79, v82
	v_fmac_f32_e32 v5, s80, v82
	v_readlane_b32 s82, v76, 3
	v_readlane_b32 s83, v60, 3
	v_readlane_b32 s84, v62, 3
	v_readlane_b32 s85, v64, 3
	v_readlane_b32 s86, v66, 3
	v_readlane_b32 s87, v68, 3
	v_readlane_b32 s88, v70, 3
	v_readlane_b32 s89, v72, 3
; __device__ __forceinline__ void prologue(const Params& p, LAS unsigned char* lds) {
;     ...
;             const int l = it >> 10, r = it & 1023, nblk = r & 15, kg = r >> 4, g = kg >> 4, c0 = (kg & 15) * 8, n = nblk * 64 + lane;
;             const float* wp = p.w_pool + ((size_t)l * 4 + g) * 128 * 128 + (size_t)c0 * 128;
;             const float* sc = p.pool_scale + l * 512 + g * 128;
;             const float* wb = p.w_br_pool + (size_t)l * 512 * DM + (size_t)(g * 128) * DM + n;
;             float a[8];
; #pragma unroll
;             for (int i = 0; i < 8; ++i) a[i] = 0.f;
; #pragma unroll 8
;             for (int d = 0; d < 128; ++d) { const float x = wb[(size_t)d * DM] * sc[d];
; #pragma unroll
;                 for (int i = 0; i < 8; ++i) a[i] += wp[i * 128 + d] * x; }
	v_readlane_b32 s90, v74, 3
	v_mul_f32_e32 v83, s82, v95
	v_fmac_f32_e32 v10, s83, v83
	v_fmac_f32_e32 v11, s84, v83
	v_fmac_f32_e32 v8, s85, v83
	v_fmac_f32_e32 v9, s86, v83
	v_fmac_f32_e32 v6, s87, v83
	v_fmac_f32_e32 v7, s88, v83
	v_fmac_f32_e32 v4, s89, v83
	v_fmac_f32_e32 v5, s90, v83
	v_readlane_b32 s72, v76, 4
	v_readlane_b32 s73, v60, 4
	v_readlane_b32 s74, v62, 4
	v_readlane_b32 s75, v64, 4
	v_readlane_b32 s76, v66, 4
	v_readlane_b32 s77, v68, 4
	v_readlane_b32 s78, v70, 4
	v_readlane_b32 s79, v72, 4
	v_readlane_b32 s80, v74, 4
	v_mul_f32_e32 v82, s72, v96
	v_fmac_f32_e32 v10, s73, v82
	v_fmac_f32_e32 v11, s74, v82
	v_fmac_f32_e32 v8, s75, v82
	v_fmac_f32_e32 v9, s76, v82
	v_fmac_f32_e32 v6, s77, v82
	v_fmac_f32_e32 v7, s78, v82
	v_fmac_f32_e32 v4, s79, v82
	v_fmac_f32_e32 v5, s80, v82
	v_readlane_b32 s82, v76, 5
	v_readlane_b32 s83, v60, 5
	v_readlane_b32 s84, v62, 5
	v_readlane_b32 s85, v64, 5
	v_readlane_b32 s86, v66, 5
	v_readlane_b32 s87, v68, 5
	v_readlane_b32 s88, v70, 5
	v_readlane_b32 s89, v72, 5
	v_readlane_b32 s90, v74, 5
	v_mul_f32_e32 v83, s82, v97
	v_fmac_f32_e32 v10, s83, v83
	v_fmac_f32_e32 v11, s84, v83
	v_fmac_f32_e32 v8, s85, v83
	v_fmac_f32_e32 v9, s86, v83
	v_fmac_f32_e32 v6, s87, v83
	v_fmac_f32_e32 v7, s88, v83
	v_fmac_f32_e32 v4, s89, v83
	v_fmac_f32_e32 v5, s90, v83
	v_readlane_b32 s72, v76, 6
	v_readlane_b32 s73, v60, 6
	v_readlane_b32 s74, v62, 6
	v_readlane_b32 s75, v64, 6
	v_readlane_b32 s76, v66, 6
	v_readlane_b32 s77, v68, 6
	v_readlane_b32 s78, v70, 6
	v_readlane_b32 s79, v72, 6
	v_readlane_b32 s80, v74, 6
	v_mul_f32_e32 v82, s72, v98
	v_fmac_f32_e32 v10, s73, v82
	v_fmac_f32_e32 v11, s74, v82
	v_fmac_f32_e32 v8, s75, v82
	v_fmac_f32_e32 v9, s76, v82
	v_fmac_f32_e32 v6, s77, v82
	v_fmac_f32_e32 v7, s78, v82
	v_fmac_f32_e32 v4, s79, v82
	v_fmac_f32_e32 v5, s80, v82
	v_readlane_b32 s82, v76, 7
	v_readlane_b32 s83, v60, 7
	v_readlane_b32 s84, v62, 7
	v_readlane_b32 s85, v64, 7
	v_readlane_b32 s86, v66, 7
	v_readlane_b32 s87, v68, 7
	v_readlane_b32 s88, v70, 7
	v_readlane_b32 s89, v72, 7
	v_readlane_b32 s90, v74, 7
	v_mul_f32_e32 v83, s82, v99
	v_fmac_f32_e32 v10, s83, v83
	v_fmac_f32_e32 v11, s84, v83
	v_fmac_f32_e32 v8, s85, v83
	v_fmac_f32_e32 v9, s86, v83
	v_fmac_f32_e32 v6, s87, v83
	v_fmac_f32_e32 v7, s88, v83
	v_fmac_f32_e32 v4, s89, v83
	v_fmac_f32_e32 v5, s90, v83
	global_load_dword v132, v[80:81], off offset:-4096
	global_load_dword v133, v[80:81], off
	v_lshl_add_u64 v[80:81], v[80:81], 0, s[68:69]
	global_load_dword v134, v[80:81], off offset:-4096
	global_load_dword v135, v[80:81], off
	v_lshl_add_u64 v[80:81], v[80:81], 0, s[68:69]
	global_load_dword v136, v[80:81], off offset:-4096
	global_load_dword v137, v[80:81], off
	v_lshl_add_u64 v[80:81], v[80:81], 0, s[68:69]
	global_load_dword v138, v[80:81], off offset:-4096
	global_load_dword v139, v[80:81], off
	v_lshl_add_u64 v[80:81], v[80:81], 0, s[68:69]
	s_waitcnt vmcnt(32)
	v_readlane_b32 s72, v76, 8
	v_readlane_b32 s73, v60, 8
	v_readlane_b32 s74, v62, 8
	v_readlane_b32 s75, v64, 8
	v_readlane_b32 s76, v66, 8
	v_readlane_b32 s77, v68, 8
	v_readlane_b32 s78, v70, 8
	v_readlane_b32 s79, v72, 8
	v_readlane_b32 s80, v74, 8
	v_mul_f32_e32 v82, s72, v100
	v_fmac_f32_e32 v10, s73, v82
	v_fmac_f32_e32 v11, s74, v82
	v_fmac_f32_e32 v8, s75, v82
	v_fmac_f32_e32 v9, s76, v82
	v_fmac_f32_e32 v6, s77, v82
	v_fmac_f32_e32 v7, s78, v82
	v_fmac_f32_e32 v4, s79, v82
	v_fmac_f32_e32 v5, s80, v82
	v_readlane_b32 s82, v76, 9
	v_readlane_b32 s83, v60, 9
	v_readlane_b32 s84, v62, 9
	v_readlane_b32 s85, v64, 9
	v_readlane_b32 s86, v66, 9
	v_readlane_b32 s87, v68, 9
	v_readlane_b32 s88, v70, 9
	v_readlane_b32 s89, v72, 9
	v_readlane_b32 s90, v74, 9
	v_mul_f32_e32 v83, s82, v101
	v_fmac_f32_e32 v10, s83, v83
	v_fmac_f32_e32 v11, s84, v83
	v_fmac_f32_e32 v8, s85, v83
	v_fmac_f32_e32 v9, s86, v83
	v_fmac_f32_e32 v6, s87, v83
	v_fmac_f32_e32 v7, s88, v83
	v_fmac_f32_e32 v4, s89, v83
	v_fmac_f32_e32 v5, s90, v83
	v_readlane_b32 s72, v76, 10
	v_readlane_b32 s73, v60, 10
	v_readlane_b32 s74, v62, 10
	v_readlane_b32 s75, v64, 10
	v_readlane_b32 s76, v66, 10
	v_readlane_b32 s77, v68, 10
	v_readlane_b32 s78, v70, 10
	v_readlane_b32 s79, v72, 10
	v_readlane_b32 s80, v74, 10
	v_mul_f32_e32 v82, s72, v102
	v_fmac_f32_e32 v10, s73, v82
	v_fmac_f32_e32 v11, s74, v82
	v_fmac_f32_e32 v8, s75, v82
	v_fmac_f32_e32 v9, s76, v82
	v_fmac_f32_e32 v6, s77, v82
	v_fmac_f32_e32 v7, s78, v82
	v_fmac_f32_e32 v4, s79, v82
	v_fmac_f32_e32 v5, s80, v82
	v_readlane_b32 s82, v76, 11
	v_readlane_b32 s83, v60, 11
	v_readlane_b32 s84, v62, 11
	v_readlane_b32 s85, v64, 11
	v_readlane_b32 s86, v66, 11
	v_readlane_b32 s87, v68, 11
	v_readlane_b32 s88, v70, 11
	v_readlane_b32 s89, v72, 11
	v_readlane_b32 s90, v74, 11
	v_mul_f32_e32 v83, s82, v103
	v_fmac_f32_e32 v10, s83, v83
	v_fmac_f32_e32 v11, s84, v83
	v_fmac_f32_e32 v8, s85, v83
	v_fmac_f32_e32 v9, s86, v83
	v_fmac_f32_e32 v6, s87, v83
	v_fmac_f32_e32 v7, s88, v83
	v_fmac_f32_e32 v4, s89, v83
	v_fmac_f32_e32 v5, s90, v83
	v_readlane_b32 s72, v76, 12
	v_readlane_b32 s73, v60, 12
	v_readlane_b32 s74, v62, 12
	v_readlane_b32 s75, v64, 12
	v_readlane_b32 s76, v66, 12
	v_readlane_b32 s77, v68, 12
	v_readlane_b32 s78, v70, 12
	v_readlane_b32 s79, v72, 12
	v_readlane_b32 s80, v74, 12
	v_mul_f32_e32 v82, s72, v104
	v_fmac_f32_e32 v10, s73, v82
	v_fmac_f32_e32 v11, s74, v82
	v_fmac_f32_e32 v8, s75, v82
	v_fmac_f32_e32 v9, s76, v82
	v_fmac_f32_e32 v6, s77, v82
	v_fmac_f32_e32 v7, s78, v82
	v_fmac_f32_e32 v4, s79, v82
	v_fmac_f32_e32 v5, s80, v82
	v_readlane_b32 s82, v76, 13
	v_readlane_b32 s83, v60, 13
	v_readlane_b32 s84, v62, 13
	v_readlane_b32 s85, v64, 13
; __device__ __forceinline__ void prologue(const Params& p, LAS unsigned char* lds) {
;     ...
;             const int l = it >> 10, r = it & 1023, nblk = r & 15, kg = r >> 4, g = kg >> 4, c0 = (kg & 15) * 8, n = nblk * 64 + lane;
;             const float* wp = p.w_pool + ((size_t)l * 4 + g) * 128 * 128 + (size_t)c0 * 128;
;             const float* sc = p.pool_scale + l * 512 + g * 128;
;             const float* wb = p.w_br_pool + (size_t)l * 512 * DM + (size_t)(g * 128) * DM + n;
;             float a[8];
; #pragma unroll
;             for (int i = 0; i < 8; ++i) a[i] = 0.f;
; #pragma unroll 8
;             for (int d = 0; d < 128; ++d) { const float x = wb[(size_t)d * DM] * sc[d];
; #pragma unroll
;                 for (int i = 0; i < 8; ++i) a[i] += wp[i * 128 + d] * x; }
	v_readlane_b32 s86, v66, 13
	v_readlane_b32 s87, v68, 13
	v_readlane_b32 s88, v70, 13
	v_readlane_b32 s89, v72, 13
	v_readlane_b32 s90, v74, 13
	v_mul_f32_e32 v83, s82, v105
	v_fmac_f32_e32 v10, s83, v83
	v_fmac_f32_e32 v11, s84, v83
	v_fmac_f32_e32 v8, s85, v83
	v_fmac_f32_e32 v9, s86, v83
	v_fmac_f32_e32 v6, s87, v83
	v_fmac_f32_e32 v7, s88, v83
	v_fmac_f32_e32 v4, s89, v83
	v_fmac_f32_e32 v5, s90, v83
	v_readlane_b32 s72, v76, 14
	v_readlane_b32 s73, v60, 14
	v_readlane_b32 s74, v62, 14
	v_readlane_b32 s75, v64, 14
	v_readlane_b32 s76, v66, 14
	v_readlane_b32 s77, v68, 14
	v_readlane_b32 s78, v70, 14
	v_readlane_b32 s79, v72, 14
	v_readlane_b32 s80, v74, 14
	v_mul_f32_e32 v82, s72, v106
	v_fmac_f32_e32 v10, s73, v82
	v_fmac_f32_e32 v11, s74, v82
	v_fmac_f32_e32 v8, s75, v82
	v_fmac_f32_e32 v9, s76, v82
	v_fmac_f32_e32 v6, s77, v82
	v_fmac_f32_e32 v7, s78, v82
	v_fmac_f32_e32 v4, s79, v82
	v_fmac_f32_e32 v5, s80, v82
	v_readlane_b32 s82, v76, 15
	v_readlane_b32 s83, v60, 15
	v_readlane_b32 s84, v62, 15
	v_readlane_b32 s85, v64, 15
	v_readlane_b32 s86, v66, 15
	v_readlane_b32 s87, v68, 15
	v_readlane_b32 s88, v70, 15
	v_readlane_b32 s89, v72, 15
	v_readlane_b32 s90, v74, 15
	v_mul_f32_e32 v83, s82, v107
	v_fmac_f32_e32 v10, s83, v83
	v_fmac_f32_e32 v11, s84, v83
	v_fmac_f32_e32 v8, s85, v83
	v_fmac_f32_e32 v9, s86, v83
	v_fmac_f32_e32 v6, s87, v83
	v_fmac_f32_e32 v7, s88, v83
	v_fmac_f32_e32 v4, s89, v83
	v_fmac_f32_e32 v5, s90, v83
	global_load_dword v140, v[80:81], off offset:-4096
	global_load_dword v141, v[80:81], off
	v_lshl_add_u64 v[80:81], v[80:81], 0, s[68:69]
	global_load_dword v142, v[80:81], off offset:-4096
	global_load_dword v143, v[80:81], off
	v_lshl_add_u64 v[80:81], v[80:81], 0, s[68:69]
	global_load_dword v144, v[80:81], off offset:-4096
	global_load_dword v145, v[80:81], off
	v_lshl_add_u64 v[80:81], v[80:81], 0, s[68:69]
	global_load_dword v146, v[80:81], off offset:-4096
	global_load_dword v147, v[80:81], off
	v_lshl_add_u64 v[80:81], v[80:81], 0, s[68:69]
	s_waitcnt vmcnt(32)
	v_readlane_b32 s72, v76, 16
	v_readlane_b32 s73, v60, 16
	v_readlane_b32 s74, v62, 16
	v_readlane_b32 s75, v64, 16
	v_readlane_b32 s76, v66, 16
	v_readlane_b32 s77, v68, 16
	v_readlane_b32 s78, v70, 16
	v_readlane_b32 s79, v72, 16
	v_readlane_b32 s80, v74, 16
	v_mul_f32_e32 v82, s72, v108
	v_fmac_f32_e32 v10, s73, v82
	v_fmac_f32_e32 v11, s74, v82
	v_fmac_f32_e32 v8, s75, v82
	v_fmac_f32_e32 v9, s76, v82
	v_fmac_f32_e32 v6, s77, v82
	v_fmac_f32_e32 v7, s78, v82
	v_fmac_f32_e32 v4, s79, v82
	v_fmac_f32_e32 v5, s80, v82
	v_readlane_b32 s82, v76, 17
	v_readlane_b32 s83, v60, 17
	v_readlane_b32 s84, v62, 17
	v_readlane_b32 s85, v64, 17
	v_readlane_b32 s86, v66, 17
	v_readlane_b32 s87, v68, 17
	v_readlane_b32 s88, v70, 17
	v_readlane_b32 s89, v72, 17
	v_readlane_b32 s90, v74, 17
	v_mul_f32_e32 v83, s82, v109
	v_fmac_f32_e32 v10, s83, v83
	v_fmac_f32_e32 v11, s84, v83
	v_fmac_f32_e32 v8, s85, v83
	v_fmac_f32_e32 v9, s86, v83
	v_fmac_f32_e32 v6, s87, v83
	v_fmac_f32_e32 v7, s88, v83
	v_fmac_f32_e32 v4, s89, v83
	v_fmac_f32_e32 v5, s90, v83
	v_readlane_b32 s72, v76, 18
	v_readlane_b32 s73, v60, 18
	v_readlane_b32 s74, v62, 18
	v_readlane_b32 s75, v64, 18
	v_readlane_b32 s76, v66, 18
	v_readlane_b32 s77, v68, 18
	v_readlane_b32 s78, v70, 18
	v_readlane_b32 s79, v72, 18
	v_readlane_b32 s80, v74, 18
	v_mul_f32_e32 v82, s72, v110
	v_fmac_f32_e32 v10, s73, v82
	v_fmac_f32_e32 v11, s74, v82
	v_fmac_f32_e32 v8, s75, v82
	v_fmac_f32_e32 v9, s76, v82
	v_fmac_f32_e32 v6, s77, v82
	v_fmac_f32_e32 v7, s78, v82
	v_fmac_f32_e32 v4, s79, v82
	v_fmac_f32_e32 v5, s80, v82
	v_readlane_b32 s82, v76, 19
	v_readlane_b32 s83, v60, 19
	v_readlane_b32 s84, v62, 19
	v_readlane_b32 s85, v64, 19
	v_readlane_b32 s86, v66, 19
	v_readlane_b32 s87, v68, 19
	v_readlane_b32 s88, v70, 19
	v_readlane_b32 s89, v72, 19
	v_readlane_b32 s90, v74, 19
	v_mul_f32_e32 v83, s82, v111
	v_fmac_f32_e32 v10, s83, v83
	v_fmac_f32_e32 v11, s84, v83
	v_fmac_f32_e32 v8, s85, v83
	v_fmac_f32_e32 v9, s86, v83
	v_fmac_f32_e32 v6, s87, v83
	v_fmac_f32_e32 v7, s88, v83
	v_fmac_f32_e32 v4, s89, v83
	v_fmac_f32_e32 v5, s90, v83
	v_readlane_b32 s72, v76, 20
	v_readlane_b32 s73, v60, 20
	v_readlane_b32 s74, v62, 20
	v_readlane_b32 s75, v64, 20
	v_readlane_b32 s76, v66, 20
	v_readlane_b32 s77, v68, 20
	v_readlane_b32 s78, v70, 20
	v_readlane_b32 s79, v72, 20
	v_readlane_b32 s80, v74, 20
	v_mul_f32_e32 v82, s72, v112
	v_fmac_f32_e32 v10, s73, v82
	v_fmac_f32_e32 v11, s74, v82
	v_fmac_f32_e32 v8, s75, v82
	v_fmac_f32_e32 v9, s76, v82
	v_fmac_f32_e32 v6, s77, v82
	v_fmac_f32_e32 v7, s78, v82
	v_fmac_f32_e32 v4, s79, v82
	v_fmac_f32_e32 v5, s80, v82
	v_readlane_b32 s82, v76, 21
	v_readlane_b32 s83, v60, 21
	v_readlane_b32 s84, v62, 21
	v_readlane_b32 s85, v64, 21
	v_readlane_b32 s86, v66, 21
	v_readlane_b32 s87, v68, 21
	v_readlane_b32 s88, v70, 21
	v_readlane_b32 s89, v72, 21
	v_readlane_b32 s90, v74, 21
	v_mul_f32_e32 v83, s82, v113
	v_fmac_f32_e32 v10, s83, v83
	v_fmac_f32_e32 v11, s84, v83
	v_fmac_f32_e32 v8, s85, v83
	v_fmac_f32_e32 v9, s86, v83
	v_fmac_f32_e32 v6, s87, v83
	v_fmac_f32_e32 v7, s88, v83
	v_fmac_f32_e32 v4, s89, v83
	v_fmac_f32_e32 v5, s90, v83
	v_readlane_b32 s72, v76, 22
	v_readlane_b32 s73, v60, 22
	v_readlane_b32 s74, v62, 22
	v_readlane_b32 s75, v64, 22
	v_readlane_b32 s76, v66, 22
	v_readlane_b32 s77, v68, 22
	v_readlane_b32 s78, v70, 22
	v_readlane_b32 s79, v72, 22
	v_readlane_b32 s80, v74, 22
	v_mul_f32_e32 v82, s72, v114
	v_fmac_f32_e32 v10, s73, v82
	v_fmac_f32_e32 v11, s74, v82
	v_fmac_f32_e32 v8, s75, v82
	v_fmac_f32_e32 v9, s76, v82
	v_fmac_f32_e32 v6, s77, v82
	v_fmac_f32_e32 v7, s78, v82
	v_fmac_f32_e32 v4, s79, v82
	v_fmac_f32_e32 v5, s80, v82
	v_readlane_b32 s82, v76, 23
	v_readlane_b32 s83, v60, 23
	v_readlane_b32 s84, v62, 23
	v_readlane_b32 s85, v64, 23
	v_readlane_b32 s86, v66, 23
	v_readlane_b32 s87, v68, 23
	v_readlane_b32 s88, v70, 23
	v_readlane_b32 s89, v72, 23
	v_readlane_b32 s90, v74, 23
	v_mul_f32_e32 v83, s82, v115
	v_fmac_f32_e32 v10, s83, v83
	v_fmac_f32_e32 v11, s84, v83
	v_fmac_f32_e32 v8, s85, v83
	v_fmac_f32_e32 v9, s86, v83
	v_fmac_f32_e32 v6, s87, v83
	v_fmac_f32_e32 v7, s88, v83
	v_fmac_f32_e32 v4, s89, v83
	v_fmac_f32_e32 v5, s90, v83
	global_load_dword v148, v[80:81], off offset:-4096
	global_load_dword v149, v[80:81], off
	v_lshl_add_u64 v[80:81], v[80:81], 0, s[68:69]
	global_load_dword v150, v[80:81], off offset:-4096
	global_load_dword v151, v[80:81], off
	v_lshl_add_u64 v[80:81], v[80:81], 0, s[68:69]
	global_load_dword v152, v[80:81], off offset:-4096
	global_load_dword v153, v[80:81], off
	v_lshl_add_u64 v[80:81], v[80:81], 0, s[68:69]
	global_load_dword v154, v[80:81], off offset:-4096
	global_load_dword v155, v[80:81], off
	v_lshl_add_u64 v[80:81], v[80:81], 0, s[68:69]
	s_waitcnt vmcnt(32)
; __device__ __forceinline__ void prologue(const Params& p, LAS unsigned char* lds) {
;     ...
;             const int l = it >> 10, r = it & 1023, nblk = r & 15, kg = r >> 4, g = kg >> 4, c0 = (kg & 15) * 8, n = nblk * 64 + lane;
;             const float* wp = p.w_pool + ((size_t)l * 4 + g) * 128 * 128 + (size_t)c0 * 128;
;             const float* sc = p.pool_scale + l * 512 + g * 128;
;             const float* wb = p.w_br_pool + (size_t)l * 512 * DM + (size_t)(g * 128) * DM + n;
;             float a[8];
; #pragma unroll
;             for (int i = 0; i < 8; ++i) a[i] = 0.f;
; #pragma unroll 8
;             for (int d = 0; d < 128; ++d) { const float x = wb[(size_t)d * DM] * sc[d];
; #pragma unroll
;                 for (int i = 0; i < 8; ++i) a[i] += wp[i * 128 + d] * x; }
	v_readlane_b32 s72, v76, 24
	v_readlane_b32 s73, v60, 24
	v_readlane_b32 s74, v62, 24
	v_readlane_b32 s75, v64, 24
	v_readlane_b32 s76, v66, 24
	v_readlane_b32 s77, v68, 24
	v_readlane_b32 s78, v70, 24
	v_readlane_b32 s79, v72, 24
	v_readlane_b32 s80, v74, 24
	v_mul_f32_e32 v82, s72, v116
	v_fmac_f32_e32 v10, s73, v82
	v_fmac_f32_e32 v11, s74, v82
	v_fmac_f32_e32 v8, s75, v82
	v_fmac_f32_e32 v9, s76, v82
	v_fmac_f32_e32 v6, s77, v82
	v_fmac_f32_e32 v7, s78, v82
	v_fmac_f32_e32 v4, s79, v82
	v_fmac_f32_e32 v5, s80, v82
	v_readlane_b32 s82, v76, 25
	v_readlane_b32 s83, v60, 25
	v_readlane_b32 s84, v62, 25
	v_readlane_b32 s85, v64, 25
	v_readlane_b32 s86, v66, 25
	v_readlane_b32 s87, v68, 25
	v_readlane_b32 s88, v70, 25
	v_readlane_b32 s89, v72, 25
	v_readlane_b32 s90, v74, 25
	v_mul_f32_e32 v83, s82, v117
	v_fmac_f32_e32 v10, s83, v83
	v_fmac_f32_e32 v11, s84, v83
	v_fmac_f32_e32 v8, s85, v83
	v_fmac_f32_e32 v9, s86, v83
	v_fmac_f32_e32 v6, s87, v83
	v_fmac_f32_e32 v7, s88, v83
	v_fmac_f32_e32 v4, s89, v83
	v_fmac_f32_e32 v5, s90, v83
	v_readlane_b32 s72, v76, 26
	v_readlane_b32 s73, v60, 26
	v_readlane_b32 s74, v62, 26
	v_readlane_b32 s75, v64, 26
	v_readlane_b32 s76, v66, 26
	v_readlane_b32 s77, v68, 26
	v_readlane_b32 s78, v70, 26
	v_readlane_b32 s79, v72, 26
	v_readlane_b32 s80, v74, 26
	v_mul_f32_e32 v82, s72, v118
	v_fmac_f32_e32 v10, s73, v82
	v_fmac_f32_e32 v11, s74, v82
	v_fmac_f32_e32 v8, s75, v82
	v_fmac_f32_e32 v9, s76, v82
	v_fmac_f32_e32 v6, s77, v82
	v_fmac_f32_e32 v7, s78, v82
	v_fmac_f32_e32 v4, s79, v82
	v_fmac_f32_e32 v5, s80, v82
	v_readlane_b32 s82, v76, 27
	v_readlane_b32 s83, v60, 27
	v_readlane_b32 s84, v62, 27
	v_readlane_b32 s85, v64, 27
	v_readlane_b32 s86, v66, 27
	v_readlane_b32 s87, v68, 27
	v_readlane_b32 s88, v70, 27
	v_readlane_b32 s89, v72, 27
	v_readlane_b32 s90, v74, 27
	v_mul_f32_e32 v83, s82, v119
	v_fmac_f32_e32 v10, s83, v83
	v_fmac_f32_e32 v11, s84, v83
	v_fmac_f32_e32 v8, s85, v83
	v_fmac_f32_e32 v9, s86, v83
	v_fmac_f32_e32 v6, s87, v83
	v_fmac_f32_e32 v7, s88, v83
	v_fmac_f32_e32 v4, s89, v83
	v_fmac_f32_e32 v5, s90, v83
	v_readlane_b32 s72, v76, 28
	v_readlane_b32 s73, v60, 28
	v_readlane_b32 s74, v62, 28
	v_readlane_b32 s75, v64, 28
	v_readlane_b32 s76, v66, 28
	v_readlane_b32 s77, v68, 28
	v_readlane_b32 s78, v70, 28
	v_readlane_b32 s79, v72, 28
	v_readlane_b32 s80, v74, 28
	v_mul_f32_e32 v82, s72, v120
	v_fmac_f32_e32 v10, s73, v82
	v_fmac_f32_e32 v11, s74, v82
	v_fmac_f32_e32 v8, s75, v82
	v_fmac_f32_e32 v9, s76, v82
	v_fmac_f32_e32 v6, s77, v82
	v_fmac_f32_e32 v7, s78, v82
	v_fmac_f32_e32 v4, s79, v82
	v_fmac_f32_e32 v5, s80, v82
	v_readlane_b32 s82, v76, 29
	v_readlane_b32 s83, v60, 29
	v_readlane_b32 s84, v62, 29
	v_readlane_b32 s85, v64, 29
	v_readlane_b32 s86, v66, 29
	v_readlane_b32 s87, v68, 29
	v_readlane_b32 s88, v70, 29
	v_readlane_b32 s89, v72, 29
	v_readlane_b32 s90, v74, 29
	v_mul_f32_e32 v83, s82, v121
	v_fmac_f32_e32 v10, s83, v83
	v_fmac_f32_e32 v11, s84, v83
	v_fmac_f32_e32 v8, s85, v83
	v_fmac_f32_e32 v9, s86, v83
	v_fmac_f32_e32 v6, s87, v83
	v_fmac_f32_e32 v7, s88, v83
	v_fmac_f32_e32 v4, s89, v83
	v_fmac_f32_e32 v5, s90, v83
	v_readlane_b32 s72, v76, 30
	v_readlane_b32 s73, v60, 30
	v_readlane_b32 s74, v62, 30
	v_readlane_b32 s75, v64, 30
	v_readlane_b32 s76, v66, 30
	v_readlane_b32 s77, v68, 30
	v_readlane_b32 s78, v70, 30
	v_readlane_b32 s79, v72, 30
	v_readlane_b32 s80, v74, 30
	v_mul_f32_e32 v82, s72, v122
	v_fmac_f32_e32 v10, s73, v82
	v_fmac_f32_e32 v11, s74, v82
	v_fmac_f32_e32 v8, s75, v82
	v_fmac_f32_e32 v9, s76, v82
	v_fmac_f32_e32 v6, s77, v82
	v_fmac_f32_e32 v7, s78, v82
	v_fmac_f32_e32 v4, s79, v82
	v_fmac_f32_e32 v5, s80, v82
	v_readlane_b32 s82, v76, 31
	v_readlane_b32 s83, v60, 31
	v_readlane_b32 s84, v62, 31
	v_readlane_b32 s85, v64, 31
	v_readlane_b32 s86, v66, 31
	v_readlane_b32 s87, v68, 31
	v_readlane_b32 s88, v70, 31
	v_readlane_b32 s89, v72, 31
	v_readlane_b32 s90, v74, 31
	v_mul_f32_e32 v83, s82, v123
	v_fmac_f32_e32 v10, s83, v83
	v_fmac_f32_e32 v11, s84, v83
	v_fmac_f32_e32 v8, s85, v83
	v_fmac_f32_e32 v9, s86, v83
	v_fmac_f32_e32 v6, s87, v83
	v_fmac_f32_e32 v7, s88, v83
	v_fmac_f32_e32 v4, s89, v83
	v_fmac_f32_e32 v5, s90, v83
	global_load_dword v156, v[80:81], off offset:-4096
	global_load_dword v157, v[80:81], off
	v_lshl_add_u64 v[80:81], v[80:81], 0, s[68:69]
	global_load_dword v158, v[80:81], off offset:-4096
	global_load_dword v159, v[80:81], off
	v_lshl_add_u64 v[80:81], v[80:81], 0, s[68:69]
	global_load_dword v160, v[80:81], off offset:-4096
	global_load_dword v161, v[80:81], off
	v_lshl_add_u64 v[80:81], v[80:81], 0, s[68:69]
	global_load_dword v162, v[80:81], off offset:-4096
	global_load_dword v163, v[80:81], off
	v_lshl_add_u64 v[80:81], v[80:81], 0, s[68:69]
	s_waitcnt vmcnt(32)
; __device__ __forceinline__ void prologue(const Params& p, LAS unsigned char* lds) {
;     ...
;             const int l = it >> 10, r = it & 1023, nblk = r & 15, kg = r >> 4, g = kg >> 4, c0 = (kg & 15) * 8, n = nblk * 64 + lane;
;             const float* wp = p.w_pool + ((size_t)l * 4 + g) * 128 * 128 + (size_t)c0 * 128;
;             const float* sc = p.pool_scale + l * 512 + g * 128;
;             const float* wb = p.w_br_pool + (size_t)l * 512 * DM + (size_t)(g * 128) * DM + n;
;             float a[8];
; #pragma unroll
;             for (int i = 0; i < 8; ++i) a[i] = 0.f;
; #pragma unroll 8
;             for (int d = 0; d < 128; ++d) { const float x = wb[(size_t)d * DM] * sc[d];
; #pragma unroll
;                 for (int i = 0; i < 8; ++i) a[i] += wp[i * 128 + d] * x; }
	v_readlane_b32 s72, v76, 32
	v_readlane_b32 s73, v60, 32
	v_readlane_b32 s74, v62, 32
	v_readlane_b32 s75, v64, 32
	v_readlane_b32 s76, v66, 32
	v_readlane_b32 s77, v68, 32
	v_readlane_b32 s78, v70, 32
	v_readlane_b32 s79, v72, 32
	v_readlane_b32 s80, v74, 32
	v_mul_f32_e32 v82, s72, v124
	v_fmac_f32_e32 v10, s73, v82
	v_fmac_f32_e32 v11, s74, v82
	v_fmac_f32_e32 v8, s75, v82
	v_fmac_f32_e32 v9, s76, v82
	v_fmac_f32_e32 v6, s77, v82
	v_fmac_f32_e32 v7, s78, v82
	v_fmac_f32_e32 v4, s79, v82
	v_fmac_f32_e32 v5, s80, v82
	v_readlane_b32 s82, v76, 33
	v_readlane_b32 s83, v60, 33
	v_readlane_b32 s84, v62, 33
	v_readlane_b32 s85, v64, 33
	v_readlane_b32 s86, v66, 33
	v_readlane_b32 s87, v68, 33
	v_readlane_b32 s88, v70, 33
	v_readlane_b32 s89, v72, 33
	v_readlane_b32 s90, v74, 33
	v_mul_f32_e32 v83, s82, v125
	v_fmac_f32_e32 v10, s83, v83
	v_fmac_f32_e32 v11, s84, v83
	v_fmac_f32_e32 v8, s85, v83
	v_fmac_f32_e32 v9, s86, v83
	v_fmac_f32_e32 v6, s87, v83
	v_fmac_f32_e32 v7, s88, v83
	v_fmac_f32_e32 v4, s89, v83
	v_fmac_f32_e32 v5, s90, v83
	v_readlane_b32 s72, v76, 34
	v_readlane_b32 s73, v60, 34
	v_readlane_b32 s74, v62, 34
	v_readlane_b32 s75, v64, 34
	v_readlane_b32 s76, v66, 34
	v_readlane_b32 s77, v68, 34
	v_readlane_b32 s78, v70, 34
	v_readlane_b32 s79, v72, 34
	v_readlane_b32 s80, v74, 34
	v_mul_f32_e32 v82, s72, v126
	v_fmac_f32_e32 v10, s73, v82
	v_fmac_f32_e32 v11, s74, v82
	v_fmac_f32_e32 v8, s75, v82
	v_fmac_f32_e32 v9, s76, v82
	v_fmac_f32_e32 v6, s77, v82
	v_fmac_f32_e32 v7, s78, v82
	v_fmac_f32_e32 v4, s79, v82
	v_fmac_f32_e32 v5, s80, v82
	v_readlane_b32 s82, v76, 35
	v_readlane_b32 s83, v60, 35
	v_readlane_b32 s84, v62, 35
	v_readlane_b32 s85, v64, 35
	v_readlane_b32 s86, v66, 35
	v_readlane_b32 s87, v68, 35
	v_readlane_b32 s88, v70, 35
	v_readlane_b32 s89, v72, 35
	v_readlane_b32 s90, v74, 35
	v_mul_f32_e32 v83, s82, v127
	v_fmac_f32_e32 v10, s83, v83
	v_fmac_f32_e32 v11, s84, v83
	v_fmac_f32_e32 v8, s85, v83
	v_fmac_f32_e32 v9, s86, v83
	v_fmac_f32_e32 v6, s87, v83
	v_fmac_f32_e32 v7, s88, v83
	v_fmac_f32_e32 v4, s89, v83
	v_fmac_f32_e32 v5, s90, v83
	v_readlane_b32 s72, v76, 36
	v_readlane_b32 s73, v60, 36
	v_readlane_b32 s74, v62, 36
	v_readlane_b32 s75, v64, 36
	v_readlane_b32 s76, v66, 36
	v_readlane_b32 s77, v68, 36
	v_readlane_b32 s78, v70, 36
	v_readlane_b32 s79, v72, 36
	v_readlane_b32 s80, v74, 36
	v_mul_f32_e32 v82, s72, v128
	v_fmac_f32_e32 v10, s73, v82
	v_fmac_f32_e32 v11, s74, v82
	v_fmac_f32_e32 v8, s75, v82
	v_fmac_f32_e32 v9, s76, v82
	v_fmac_f32_e32 v6, s77, v82
	v_fmac_f32_e32 v7, s78, v82
	v_fmac_f32_e32 v4, s79, v82
	v_fmac_f32_e32 v5, s80, v82
	v_readlane_b32 s82, v76, 37
	v_readlane_b32 s83, v60, 37
	v_readlane_b32 s84, v62, 37
	v_readlane_b32 s85, v64, 37
	v_readlane_b32 s86, v66, 37
	v_readlane_b32 s87, v68, 37
	v_readlane_b32 s88, v70, 37
	v_readlane_b32 s89, v72, 37
	v_readlane_b32 s90, v74, 37
	v_mul_f32_e32 v83, s82, v129
	v_fmac_f32_e32 v10, s83, v83
	v_fmac_f32_e32 v11, s84, v83
	v_fmac_f32_e32 v8, s85, v83
	v_fmac_f32_e32 v9, s86, v83
	v_fmac_f32_e32 v6, s87, v83
	v_fmac_f32_e32 v7, s88, v83
	v_fmac_f32_e32 v4, s89, v83
	v_fmac_f32_e32 v5, s90, v83
	v_readlane_b32 s72, v76, 38
	v_readlane_b32 s73, v60, 38
	v_readlane_b32 s74, v62, 38
	v_readlane_b32 s75, v64, 38
	v_readlane_b32 s76, v66, 38
	v_readlane_b32 s77, v68, 38
	v_readlane_b32 s78, v70, 38
	v_readlane_b32 s79, v72, 38
	v_readlane_b32 s80, v74, 38
	v_mul_f32_e32 v82, s72, v130
	v_fmac_f32_e32 v10, s73, v82
	v_fmac_f32_e32 v11, s74, v82
	v_fmac_f32_e32 v8, s75, v82
	v_fmac_f32_e32 v9, s76, v82
	v_fmac_f32_e32 v6, s77, v82
	v_fmac_f32_e32 v7, s78, v82
	v_fmac_f32_e32 v4, s79, v82
	v_fmac_f32_e32 v5, s80, v82
	v_readlane_b32 s82, v76, 39
	v_readlane_b32 s83, v60, 39
	v_readlane_b32 s84, v62, 39
	v_readlane_b32 s85, v64, 39
	v_readlane_b32 s86, v66, 39
	v_readlane_b32 s87, v68, 39
	v_readlane_b32 s88, v70, 39
	v_readlane_b32 s89, v72, 39
	v_readlane_b32 s90, v74, 39
	v_mul_f32_e32 v83, s82, v131
	v_fmac_f32_e32 v10, s83, v83
	v_fmac_f32_e32 v11, s84, v83
	v_fmac_f32_e32 v8, s85, v83
	v_fmac_f32_e32 v9, s86, v83
	v_fmac_f32_e32 v6, s87, v83
	v_fmac_f32_e32 v7, s88, v83
	v_fmac_f32_e32 v4, s89, v83
	v_fmac_f32_e32 v5, s90, v83
	global_load_dword v164, v[80:81], off offset:-4096
	global_load_dword v165, v[80:81], off
	v_lshl_add_u64 v[80:81], v[80:81], 0, s[68:69]
	global_load_dword v166, v[80:81], off offset:-4096
	global_load_dword v167, v[80:81], off
	v_lshl_add_u64 v[80:81], v[80:81], 0, s[68:69]
	global_load_dword v168, v[80:81], off offset:-4096
	global_load_dword v169, v[80:81], off
	v_lshl_add_u64 v[80:81], v[80:81], 0, s[68:69]
	global_load_dword v170, v[80:81], off offset:-4096
	global_load_dword v171, v[80:81], off
	v_lshl_add_u64 v[80:81], v[80:81], 0, s[68:69]
	s_waitcnt vmcnt(32)
; __device__ __forceinline__ void prologue(const Params& p, LAS unsigned char* lds) {
;     ...
;             const int l = it >> 10, r = it & 1023, nblk = r & 15, kg = r >> 4, g = kg >> 4, c0 = (kg & 15) * 8, n = nblk * 64 + lane;
;             const float* wp = p.w_pool + ((size_t)l * 4 + g) * 128 * 128 + (size_t)c0 * 128;
;             const float* sc = p.pool_scale + l * 512 + g * 128;
;             const float* wb = p.w_br_pool + (size_t)l * 512 * DM + (size_t)(g * 128) * DM + n;
;             float a[8];
; #pragma unroll
;             for (int i = 0; i < 8; ++i) a[i] = 0.f;
; #pragma unroll 8
;             for (int d = 0; d < 128; ++d) { const float x = wb[(size_t)d * DM] * sc[d];
; #pragma unroll
;                 for (int i = 0; i < 8; ++i) a[i] += wp[i * 128 + d] * x; }
	v_readlane_b32 s72, v76, 40
	v_readlane_b32 s73, v60, 40
	v_readlane_b32 s74, v62, 40
	v_readlane_b32 s75, v64, 40
	v_readlane_b32 s76, v66, 40
	v_readlane_b32 s77, v68, 40
	v_readlane_b32 s78, v70, 40
	v_readlane_b32 s79, v72, 40
	v_readlane_b32 s80, v74, 40
	v_mul_f32_e32 v82, s72, v132
	v_fmac_f32_e32 v10, s73, v82
	v_fmac_f32_e32 v11, s74, v82
	v_fmac_f32_e32 v8, s75, v82
	v_fmac_f32_e32 v9, s76, v82
	v_fmac_f32_e32 v6, s77, v82
	v_fmac_f32_e32 v7, s78, v82
	v_fmac_f32_e32 v4, s79, v82
	v_fmac_f32_e32 v5, s80, v82
	v_readlane_b32 s82, v76, 41
	v_readlane_b32 s83, v60, 41
	v_readlane_b32 s84, v62, 41
	v_readlane_b32 s85, v64, 41
	v_readlane_b32 s86, v66, 41
	v_readlane_b32 s87, v68, 41
	v_readlane_b32 s88, v70, 41
	v_readlane_b32 s89, v72, 41
	v_readlane_b32 s90, v74, 41
	v_mul_f32_e32 v83, s82, v133
	v_fmac_f32_e32 v10, s83, v83
	v_fmac_f32_e32 v11, s84, v83
	v_fmac_f32_e32 v8, s85, v83
	v_fmac_f32_e32 v9, s86, v83
	v_fmac_f32_e32 v6, s87, v83
	v_fmac_f32_e32 v7, s88, v83
	v_fmac_f32_e32 v4, s89, v83
	v_fmac_f32_e32 v5, s90, v83
	v_readlane_b32 s72, v76, 42
	v_readlane_b32 s73, v60, 42
	v_readlane_b32 s74, v62, 42
	v_readlane_b32 s75, v64, 42
	v_readlane_b32 s76, v66, 42
	v_readlane_b32 s77, v68, 42
	v_readlane_b32 s78, v70, 42
	v_readlane_b32 s79, v72, 42
	v_readlane_b32 s80, v74, 42
	v_mul_f32_e32 v82, s72, v134
	v_fmac_f32_e32 v10, s73, v82
	v_fmac_f32_e32 v11, s74, v82
	v_fmac_f32_e32 v8, s75, v82
	v_fmac_f32_e32 v9, s76, v82
	v_fmac_f32_e32 v6, s77, v82
	v_fmac_f32_e32 v7, s78, v82
	v_fmac_f32_e32 v4, s79, v82
	v_fmac_f32_e32 v5, s80, v82
	v_readlane_b32 s82, v76, 43
	v_readlane_b32 s83, v60, 43
	v_readlane_b32 s84, v62, 43
	v_readlane_b32 s85, v64, 43
	v_readlane_b32 s86, v66, 43
	v_readlane_b32 s87, v68, 43
	v_readlane_b32 s88, v70, 43
	v_readlane_b32 s89, v72, 43
	v_readlane_b32 s90, v74, 43
	v_mul_f32_e32 v83, s82, v135
	v_fmac_f32_e32 v10, s83, v83
	v_fmac_f32_e32 v11, s84, v83
	v_fmac_f32_e32 v8, s85, v83
	v_fmac_f32_e32 v9, s86, v83
	v_fmac_f32_e32 v6, s87, v83
	v_fmac_f32_e32 v7, s88, v83
	v_fmac_f32_e32 v4, s89, v83
	v_fmac_f32_e32 v5, s90, v83
	v_readlane_b32 s72, v76, 44
	v_readlane_b32 s73, v60, 44
	v_readlane_b32 s74, v62, 44
	v_readlane_b32 s75, v64, 44
	v_readlane_b32 s76, v66, 44
	v_readlane_b32 s77, v68, 44
	v_readlane_b32 s78, v70, 44
	v_readlane_b32 s79, v72, 44
	v_readlane_b32 s80, v74, 44
	v_mul_f32_e32 v82, s72, v136
	v_fmac_f32_e32 v10, s73, v82
	v_fmac_f32_e32 v11, s74, v82
	v_fmac_f32_e32 v8, s75, v82
	v_fmac_f32_e32 v9, s76, v82
	v_fmac_f32_e32 v6, s77, v82
	v_fmac_f32_e32 v7, s78, v82
	v_fmac_f32_e32 v4, s79, v82
	v_fmac_f32_e32 v5, s80, v82
	v_readlane_b32 s82, v76, 45
	v_readlane_b32 s83, v60, 45
	v_readlane_b32 s84, v62, 45
	v_readlane_b32 s85, v64, 45
	v_readlane_b32 s86, v66, 45
	v_readlane_b32 s87, v68, 45
	v_readlane_b32 s88, v70, 45
	v_readlane_b32 s89, v72, 45
	v_readlane_b32 s90, v74, 45
	v_mul_f32_e32 v83, s82, v137
	v_fmac_f32_e32 v10, s83, v83
	v_fmac_f32_e32 v11, s84, v83
	v_fmac_f32_e32 v8, s85, v83
	v_fmac_f32_e32 v9, s86, v83
	v_fmac_f32_e32 v6, s87, v83
	v_fmac_f32_e32 v7, s88, v83
	v_fmac_f32_e32 v4, s89, v83
	v_fmac_f32_e32 v5, s90, v83
	v_readlane_b32 s72, v76, 46
	v_readlane_b32 s73, v60, 46
	v_readlane_b32 s74, v62, 46
	v_readlane_b32 s75, v64, 46
	v_readlane_b32 s76, v66, 46
	v_readlane_b32 s77, v68, 46
	v_readlane_b32 s78, v70, 46
	v_readlane_b32 s79, v72, 46
	v_readlane_b32 s80, v74, 46
	v_mul_f32_e32 v82, s72, v138
	v_fmac_f32_e32 v10, s73, v82
	v_fmac_f32_e32 v11, s74, v82
	v_fmac_f32_e32 v8, s75, v82
	v_fmac_f32_e32 v9, s76, v82
	v_fmac_f32_e32 v6, s77, v82
	v_fmac_f32_e32 v7, s78, v82
	v_fmac_f32_e32 v4, s79, v82
	v_fmac_f32_e32 v5, s80, v82
	v_readlane_b32 s82, v76, 47
	v_readlane_b32 s83, v60, 47
	v_readlane_b32 s84, v62, 47
	v_readlane_b32 s85, v64, 47
	v_readlane_b32 s86, v66, 47
	v_readlane_b32 s87, v68, 47
	v_readlane_b32 s88, v70, 47
	v_readlane_b32 s89, v72, 47
	v_readlane_b32 s90, v74, 47
	v_mul_f32_e32 v83, s82, v139
	v_fmac_f32_e32 v10, s83, v83
	v_fmac_f32_e32 v11, s84, v83
	v_fmac_f32_e32 v8, s85, v83
	v_fmac_f32_e32 v9, s86, v83
	v_fmac_f32_e32 v6, s87, v83
	v_fmac_f32_e32 v7, s88, v83
	v_fmac_f32_e32 v4, s89, v83
	v_fmac_f32_e32 v5, s90, v83
	global_load_dword v172, v[80:81], off offset:-4096
	global_load_dword v173, v[80:81], off
	v_lshl_add_u64 v[80:81], v[80:81], 0, s[68:69]
	global_load_dword v174, v[80:81], off offset:-4096
	global_load_dword v175, v[80:81], off
	v_lshl_add_u64 v[80:81], v[80:81], 0, s[68:69]
	global_load_dword v176, v[80:81], off offset:-4096
	global_load_dword v177, v[80:81], off
	v_lshl_add_u64 v[80:81], v[80:81], 0, s[68:69]
	global_load_dword v178, v[80:81], off offset:-4096
	global_load_dword v179, v[80:81], off
	v_lshl_add_u64 v[80:81], v[80:81], 0, s[68:69]
	s_waitcnt vmcnt(32)
; __device__ __forceinline__ void prologue(const Params& p, LAS unsigned char* lds) {
;     ...
;             const int l = it >> 10, r = it & 1023, nblk = r & 15, kg = r >> 4, g = kg >> 4, c0 = (kg & 15) * 8, n = nblk * 64 + lane;
;             const float* wp = p.w_pool + ((size_t)l * 4 + g) * 128 * 128 + (size_t)c0 * 128;
;             const float* sc = p.pool_scale + l * 512 + g * 128;
;             const float* wb = p.w_br_pool + (size_t)l * 512 * DM + (size_t)(g * 128) * DM + n;
;             float a[8];
; #pragma unroll
;             for (int i = 0; i < 8; ++i) a[i] = 0.f;
; #pragma unroll 8
;             for (int d = 0; d < 128; ++d) { const float x = wb[(size_t)d * DM] * sc[d];
; #pragma unroll
;                 for (int i = 0; i < 8; ++i) a[i] += wp[i * 128 + d] * x; }
	v_readlane_b32 s72, v76, 48
	v_readlane_b32 s73, v60, 48
	v_readlane_b32 s74, v62, 48
	v_readlane_b32 s75, v64, 48
	v_readlane_b32 s76, v66, 48
	v_readlane_b32 s77, v68, 48
	v_readlane_b32 s78, v70, 48
	v_readlane_b32 s79, v72, 48
	v_readlane_b32 s80, v74, 48
	v_mul_f32_e32 v82, s72, v140
	v_fmac_f32_e32 v10, s73, v82
	v_fmac_f32_e32 v11, s74, v82
	v_fmac_f32_e32 v8, s75, v82
	v_fmac_f32_e32 v9, s76, v82
	v_fmac_f32_e32 v6, s77, v82
	v_fmac_f32_e32 v7, s78, v82
	v_fmac_f32_e32 v4, s79, v82
	v_fmac_f32_e32 v5, s80, v82
	v_readlane_b32 s82, v76, 49
	v_readlane_b32 s83, v60, 49
	v_readlane_b32 s84, v62, 49
	v_readlane_b32 s85, v64, 49
	v_readlane_b32 s86, v66, 49
	v_readlane_b32 s87, v68, 49
	v_readlane_b32 s88, v70, 49
	v_readlane_b32 s89, v72, 49
	v_readlane_b32 s90, v74, 49
	v_mul_f32_e32 v83, s82, v141
	v_fmac_f32_e32 v10, s83, v83
	v_fmac_f32_e32 v11, s84, v83
	v_fmac_f32_e32 v8, s85, v83
	v_fmac_f32_e32 v9, s86, v83
	v_fmac_f32_e32 v6, s87, v83
	v_fmac_f32_e32 v7, s88, v83
	v_fmac_f32_e32 v4, s89, v83
	v_fmac_f32_e32 v5, s90, v83
	v_readlane_b32 s72, v76, 50
	v_readlane_b32 s73, v60, 50
	v_readlane_b32 s74, v62, 50
	v_readlane_b32 s75, v64, 50
	v_readlane_b32 s76, v66, 50
	v_readlane_b32 s77, v68, 50
	v_readlane_b32 s78, v70, 50
	v_readlane_b32 s79, v72, 50
	v_readlane_b32 s80, v74, 50
	v_mul_f32_e32 v82, s72, v142
	v_fmac_f32_e32 v10, s73, v82
	v_fmac_f32_e32 v11, s74, v82
	v_fmac_f32_e32 v8, s75, v82
	v_fmac_f32_e32 v9, s76, v82
	v_fmac_f32_e32 v6, s77, v82
	v_fmac_f32_e32 v7, s78, v82
	v_fmac_f32_e32 v4, s79, v82
	v_fmac_f32_e32 v5, s80, v82
	v_readlane_b32 s82, v76, 51
	v_readlane_b32 s83, v60, 51
	v_readlane_b32 s84, v62, 51
	v_readlane_b32 s85, v64, 51
	v_readlane_b32 s86, v66, 51
	v_readlane_b32 s87, v68, 51
	v_readlane_b32 s88, v70, 51
	v_readlane_b32 s89, v72, 51
	v_readlane_b32 s90, v74, 51
	v_mul_f32_e32 v83, s82, v143
	v_fmac_f32_e32 v10, s83, v83
	v_fmac_f32_e32 v11, s84, v83
	v_fmac_f32_e32 v8, s85, v83
	v_fmac_f32_e32 v9, s86, v83
	v_fmac_f32_e32 v6, s87, v83
	v_fmac_f32_e32 v7, s88, v83
	v_fmac_f32_e32 v4, s89, v83
	v_fmac_f32_e32 v5, s90, v83
	v_readlane_b32 s72, v76, 52
	v_readlane_b32 s73, v60, 52
	v_readlane_b32 s74, v62, 52
	v_readlane_b32 s75, v64, 52
	v_readlane_b32 s76, v66, 52
	v_readlane_b32 s77, v68, 52
	v_readlane_b32 s78, v70, 52
	v_readlane_b32 s79, v72, 52
	v_readlane_b32 s80, v74, 52
	v_mul_f32_e32 v82, s72, v144
	v_fmac_f32_e32 v10, s73, v82
	v_fmac_f32_e32 v11, s74, v82
	v_fmac_f32_e32 v8, s75, v82
	v_fmac_f32_e32 v9, s76, v82
	v_fmac_f32_e32 v6, s77, v82
	v_fmac_f32_e32 v7, s78, v82
	v_fmac_f32_e32 v4, s79, v82
	v_fmac_f32_e32 v5, s80, v82
	v_readlane_b32 s82, v76, 53
	v_readlane_b32 s83, v60, 53
	v_readlane_b32 s84, v62, 53
	v_readlane_b32 s85, v64, 53
	v_readlane_b32 s86, v66, 53
	v_readlane_b32 s87, v68, 53
	v_readlane_b32 s88, v70, 53
	v_readlane_b32 s89, v72, 53
	v_readlane_b32 s90, v74, 53
	v_mul_f32_e32 v83, s82, v145
	v_fmac_f32_e32 v10, s83, v83
	v_fmac_f32_e32 v11, s84, v83
	v_fmac_f32_e32 v8, s85, v83
	v_fmac_f32_e32 v9, s86, v83
	v_fmac_f32_e32 v6, s87, v83
	v_fmac_f32_e32 v7, s88, v83
	v_fmac_f32_e32 v4, s89, v83
	v_fmac_f32_e32 v5, s90, v83
	v_readlane_b32 s72, v76, 54
	v_readlane_b32 s73, v60, 54
	v_readlane_b32 s74, v62, 54
	v_readlane_b32 s75, v64, 54
	v_readlane_b32 s76, v66, 54
	v_readlane_b32 s77, v68, 54
	v_readlane_b32 s78, v70, 54
	v_readlane_b32 s79, v72, 54
	v_readlane_b32 s80, v74, 54
	v_mul_f32_e32 v82, s72, v146
	v_fmac_f32_e32 v10, s73, v82
	v_fmac_f32_e32 v11, s74, v82
	v_fmac_f32_e32 v8, s75, v82
	v_fmac_f32_e32 v9, s76, v82
	v_fmac_f32_e32 v6, s77, v82
	v_fmac_f32_e32 v7, s78, v82
	v_fmac_f32_e32 v4, s79, v82
	v_fmac_f32_e32 v5, s80, v82
	v_readlane_b32 s82, v76, 55
	v_readlane_b32 s83, v60, 55
	v_readlane_b32 s84, v62, 55
	v_readlane_b32 s85, v64, 55
	v_readlane_b32 s86, v66, 55
	v_readlane_b32 s87, v68, 55
	v_readlane_b32 s88, v70, 55
	v_readlane_b32 s89, v72, 55
	v_readlane_b32 s90, v74, 55
	v_mul_f32_e32 v83, s82, v147
	v_fmac_f32_e32 v10, s83, v83
	v_fmac_f32_e32 v11, s84, v83
	v_fmac_f32_e32 v8, s85, v83
	v_fmac_f32_e32 v9, s86, v83
	v_fmac_f32_e32 v6, s87, v83
	v_fmac_f32_e32 v7, s88, v83
	v_fmac_f32_e32 v4, s89, v83
	v_fmac_f32_e32 v5, s90, v83
	global_load_dword v180, v[80:81], off offset:-4096
	global_load_dword v181, v[80:81], off
	v_lshl_add_u64 v[80:81], v[80:81], 0, s[68:69]
	global_load_dword v182, v[80:81], off offset:-4096
	global_load_dword v183, v[80:81], off
	v_lshl_add_u64 v[80:81], v[80:81], 0, s[68:69]
	global_load_dword v184, v[80:81], off offset:-4096
	global_load_dword v185, v[80:81], off
	v_lshl_add_u64 v[80:81], v[80:81], 0, s[68:69]
	global_load_dword v186, v[80:81], off offset:-4096
	global_load_dword v187, v[80:81], off
	v_lshl_add_u64 v[80:81], v[80:81], 0, s[68:69]
	s_waitcnt vmcnt(32)
; __device__ __forceinline__ void prologue(const Params& p, LAS unsigned char* lds) {
;     ...
;             const int l = it >> 10, r = it & 1023, nblk = r & 15, kg = r >> 4, g = kg >> 4, c0 = (kg & 15) * 8, n = nblk * 64 + lane;
;             const float* wp = p.w_pool + ((size_t)l * 4 + g) * 128 * 128 + (size_t)c0 * 128;
;             const float* sc = p.pool_scale + l * 512 + g * 128;
;             const float* wb = p.w_br_pool + (size_t)l * 512 * DM + (size_t)(g * 128) * DM + n;
;             float a[8];
; #pragma unroll
;             for (int i = 0; i < 8; ++i) a[i] = 0.f;
; #pragma unroll 8
;             for (int d = 0; d < 128; ++d) { const float x = wb[(size_t)d * DM] * sc[d];
; #pragma unroll
;                 for (int i = 0; i < 8; ++i) a[i] += wp[i * 128 + d] * x; }
	v_readlane_b32 s72, v76, 56
	v_readlane_b32 s73, v60, 56
	v_readlane_b32 s74, v62, 56
	v_readlane_b32 s75, v64, 56
	v_readlane_b32 s76, v66, 56
	v_readlane_b32 s77, v68, 56
	v_readlane_b32 s78, v70, 56
	v_readlane_b32 s79, v72, 56
	v_readlane_b32 s80, v74, 56
	v_mul_f32_e32 v82, s72, v148
	v_fmac_f32_e32 v10, s73, v82
	v_fmac_f32_e32 v11, s74, v82
	v_fmac_f32_e32 v8, s75, v82
	v_fmac_f32_e32 v9, s76, v82
	v_fmac_f32_e32 v6, s77, v82
	v_fmac_f32_e32 v7, s78, v82
	v_fmac_f32_e32 v4, s79, v82
	v_fmac_f32_e32 v5, s80, v82
	v_readlane_b32 s82, v76, 57
	v_readlane_b32 s83, v60, 57
	v_readlane_b32 s84, v62, 57
	v_readlane_b32 s85, v64, 57
	v_readlane_b32 s86, v66, 57
	v_readlane_b32 s87, v68, 57
	v_readlane_b32 s88, v70, 57
	v_readlane_b32 s89, v72, 57
	v_readlane_b32 s90, v74, 57
	v_mul_f32_e32 v83, s82, v149
	v_fmac_f32_e32 v10, s83, v83
	v_fmac_f32_e32 v11, s84, v83
	v_fmac_f32_e32 v8, s85, v83
	v_fmac_f32_e32 v9, s86, v83
	v_fmac_f32_e32 v6, s87, v83
	v_fmac_f32_e32 v7, s88, v83
	v_fmac_f32_e32 v4, s89, v83
	v_fmac_f32_e32 v5, s90, v83
	v_readlane_b32 s72, v76, 58
	v_readlane_b32 s73, v60, 58
	v_readlane_b32 s74, v62, 58
	v_readlane_b32 s75, v64, 58
	v_readlane_b32 s76, v66, 58
	v_readlane_b32 s77, v68, 58
	v_readlane_b32 s78, v70, 58
	v_readlane_b32 s79, v72, 58
	v_readlane_b32 s80, v74, 58
	v_mul_f32_e32 v82, s72, v150
	v_fmac_f32_e32 v10, s73, v82
	v_fmac_f32_e32 v11, s74, v82
	v_fmac_f32_e32 v8, s75, v82
	v_fmac_f32_e32 v9, s76, v82
	v_fmac_f32_e32 v6, s77, v82
	v_fmac_f32_e32 v7, s78, v82
	v_fmac_f32_e32 v4, s79, v82
	v_fmac_f32_e32 v5, s80, v82
	v_readlane_b32 s82, v76, 59
	v_readlane_b32 s83, v60, 59
	v_readlane_b32 s84, v62, 59
	v_readlane_b32 s85, v64, 59
	v_readlane_b32 s86, v66, 59
	v_readlane_b32 s87, v68, 59
	v_readlane_b32 s88, v70, 59
	v_readlane_b32 s89, v72, 59
	v_readlane_b32 s90, v74, 59
	v_mul_f32_e32 v83, s82, v151
	v_fmac_f32_e32 v10, s83, v83
	v_fmac_f32_e32 v11, s84, v83
	v_fmac_f32_e32 v8, s85, v83
	v_fmac_f32_e32 v9, s86, v83
	v_fmac_f32_e32 v6, s87, v83
	v_fmac_f32_e32 v7, s88, v83
	v_fmac_f32_e32 v4, s89, v83
	v_fmac_f32_e32 v5, s90, v83
	v_readlane_b32 s72, v76, 60
	v_readlane_b32 s73, v60, 60
	v_readlane_b32 s74, v62, 60
	v_readlane_b32 s75, v64, 60
	v_readlane_b32 s76, v66, 60
	v_readlane_b32 s77, v68, 60
	v_readlane_b32 s78, v70, 60
	v_readlane_b32 s79, v72, 60
	v_readlane_b32 s80, v74, 60
	v_mul_f32_e32 v82, s72, v152
	v_fmac_f32_e32 v10, s73, v82
	v_fmac_f32_e32 v11, s74, v82
	v_fmac_f32_e32 v8, s75, v82
	v_fmac_f32_e32 v9, s76, v82
	v_fmac_f32_e32 v6, s77, v82
	v_fmac_f32_e32 v7, s78, v82
	v_fmac_f32_e32 v4, s79, v82
	v_fmac_f32_e32 v5, s80, v82
	v_readlane_b32 s82, v76, 61
	v_readlane_b32 s83, v60, 61
	v_readlane_b32 s84, v62, 61
	v_readlane_b32 s85, v64, 61
	v_readlane_b32 s86, v66, 61
	v_readlane_b32 s87, v68, 61
	v_readlane_b32 s88, v70, 61
	v_readlane_b32 s89, v72, 61
	v_readlane_b32 s90, v74, 61
	v_mul_f32_e32 v83, s82, v153
	v_fmac_f32_e32 v10, s83, v83
	v_fmac_f32_e32 v11, s84, v83
	v_fmac_f32_e32 v8, s85, v83
	v_fmac_f32_e32 v9, s86, v83
	v_fmac_f32_e32 v6, s87, v83
	v_fmac_f32_e32 v7, s88, v83
	v_fmac_f32_e32 v4, s89, v83
	v_fmac_f32_e32 v5, s90, v83
	v_readlane_b32 s72, v76, 62
	v_readlane_b32 s73, v60, 62
	v_readlane_b32 s74, v62, 62
	v_readlane_b32 s75, v64, 62
	v_readlane_b32 s76, v66, 62
	v_readlane_b32 s77, v68, 62
	v_readlane_b32 s78, v70, 62
	v_readlane_b32 s79, v72, 62
	v_readlane_b32 s80, v74, 62
	v_mul_f32_e32 v82, s72, v154
	v_fmac_f32_e32 v10, s73, v82
	v_fmac_f32_e32 v11, s74, v82
	v_fmac_f32_e32 v8, s75, v82
	v_fmac_f32_e32 v9, s76, v82
	v_fmac_f32_e32 v6, s77, v82
	v_fmac_f32_e32 v7, s78, v82
	v_fmac_f32_e32 v4, s79, v82
	v_fmac_f32_e32 v5, s80, v82
	v_readlane_b32 s82, v76, 63
	v_readlane_b32 s83, v60, 63
	v_readlane_b32 s84, v62, 63
	v_readlane_b32 s85, v64, 63
	v_readlane_b32 s86, v66, 63
	v_readlane_b32 s87, v68, 63
	v_readlane_b32 s88, v70, 63
	v_readlane_b32 s89, v72, 63
	v_readlane_b32 s90, v74, 63
	v_mul_f32_e32 v83, s82, v155
	v_fmac_f32_e32 v10, s83, v83
	v_fmac_f32_e32 v11, s84, v83
	v_fmac_f32_e32 v8, s85, v83
	v_fmac_f32_e32 v9, s86, v83
	v_fmac_f32_e32 v6, s87, v83
	v_fmac_f32_e32 v7, s88, v83
	v_fmac_f32_e32 v4, s89, v83
	v_fmac_f32_e32 v5, s90, v83
	global_load_dword v188, v[80:81], off offset:-4096
	global_load_dword v189, v[80:81], off
	v_lshl_add_u64 v[80:81], v[80:81], 0, s[68:69]
	global_load_dword v190, v[80:81], off offset:-4096
	global_load_dword v191, v[80:81], off
	v_lshl_add_u64 v[80:81], v[80:81], 0, s[68:69]
	global_load_dword v192, v[80:81], off offset:-4096
	global_load_dword v193, v[80:81], off
	v_lshl_add_u64 v[80:81], v[80:81], 0, s[68:69]
	global_load_dword v194, v[80:81], off offset:-4096
	global_load_dword v195, v[80:81], off
	v_lshl_add_u64 v[80:81], v[80:81], 0, s[68:69]
	s_waitcnt vmcnt(32)
; __device__ __forceinline__ void prologue(const Params& p, LAS unsigned char* lds) {
;     ...
;             const int l = it >> 10, r = it & 1023, nblk = r & 15, kg = r >> 4, g = kg >> 4, c0 = (kg & 15) * 8, n = nblk * 64 + lane;
;             const float* wp = p.w_pool + ((size_t)l * 4 + g) * 128 * 128 + (size_t)c0 * 128;
;             const float* sc = p.pool_scale + l * 512 + g * 128;
;             const float* wb = p.w_br_pool + (size_t)l * 512 * DM + (size_t)(g * 128) * DM + n;
;             float a[8];
; #pragma unroll
;             for (int i = 0; i < 8; ++i) a[i] = 0.f;
; #pragma unroll 8
;             for (int d = 0; d < 128; ++d) { const float x = wb[(size_t)d * DM] * sc[d];
; #pragma unroll
;                 for (int i = 0; i < 8; ++i) a[i] += wp[i * 128 + d] * x; }
	v_readlane_b32 s72, v77, 0
	v_readlane_b32 s73, v61, 0
	v_readlane_b32 s74, v63, 0
	v_readlane_b32 s75, v65, 0
	v_readlane_b32 s76, v67, 0
	v_readlane_b32 s77, v69, 0
	v_readlane_b32 s78, v71, 0
	v_readlane_b32 s79, v73, 0
	v_readlane_b32 s80, v75, 0
	v_mul_f32_e32 v82, s72, v156
	v_fmac_f32_e32 v10, s73, v82
	v_fmac_f32_e32 v11, s74, v82
	v_fmac_f32_e32 v8, s75, v82
	v_fmac_f32_e32 v9, s76, v82
	v_fmac_f32_e32 v6, s77, v82
	v_fmac_f32_e32 v7, s78, v82
	v_fmac_f32_e32 v4, s79, v82
	v_fmac_f32_e32 v5, s80, v82
	v_readlane_b32 s82, v77, 1
	v_readlane_b32 s83, v61, 1
	v_readlane_b32 s84, v63, 1
	v_readlane_b32 s85, v65, 1
	v_readlane_b32 s86, v67, 1
	v_readlane_b32 s87, v69, 1
	v_readlane_b32 s88, v71, 1
	v_readlane_b32 s89, v73, 1
	v_readlane_b32 s90, v75, 1
	v_mul_f32_e32 v83, s82, v157
	v_fmac_f32_e32 v10, s83, v83
	v_fmac_f32_e32 v11, s84, v83
	v_fmac_f32_e32 v8, s85, v83
	v_fmac_f32_e32 v9, s86, v83
	v_fmac_f32_e32 v6, s87, v83
	v_fmac_f32_e32 v7, s88, v83
	v_fmac_f32_e32 v4, s89, v83
	v_fmac_f32_e32 v5, s90, v83
	v_readlane_b32 s72, v77, 2
	v_readlane_b32 s73, v61, 2
	v_readlane_b32 s74, v63, 2
	v_readlane_b32 s75, v65, 2
	v_readlane_b32 s76, v67, 2
	v_readlane_b32 s77, v69, 2
	v_readlane_b32 s78, v71, 2
	v_readlane_b32 s79, v73, 2
	v_readlane_b32 s80, v75, 2
	v_mul_f32_e32 v82, s72, v158
	v_fmac_f32_e32 v10, s73, v82
	v_fmac_f32_e32 v11, s74, v82
	v_fmac_f32_e32 v8, s75, v82
	v_fmac_f32_e32 v9, s76, v82
	v_fmac_f32_e32 v6, s77, v82
	v_fmac_f32_e32 v7, s78, v82
	v_fmac_f32_e32 v4, s79, v82
	v_fmac_f32_e32 v5, s80, v82
	v_readlane_b32 s82, v77, 3
	v_readlane_b32 s83, v61, 3
	v_readlane_b32 s84, v63, 3
	v_readlane_b32 s85, v65, 3
	v_readlane_b32 s86, v67, 3
	v_readlane_b32 s87, v69, 3
	v_readlane_b32 s88, v71, 3
	v_readlane_b32 s89, v73, 3
	v_readlane_b32 s90, v75, 3
	v_mul_f32_e32 v83, s82, v159
	v_fmac_f32_e32 v10, s83, v83
	v_fmac_f32_e32 v11, s84, v83
	v_fmac_f32_e32 v8, s85, v83
	v_fmac_f32_e32 v9, s86, v83
	v_fmac_f32_e32 v6, s87, v83
	v_fmac_f32_e32 v7, s88, v83
	v_fmac_f32_e32 v4, s89, v83
	v_fmac_f32_e32 v5, s90, v83
	v_readlane_b32 s72, v77, 4
	v_readlane_b32 s73, v61, 4
	v_readlane_b32 s74, v63, 4
	v_readlane_b32 s75, v65, 4
	v_readlane_b32 s76, v67, 4
	v_readlane_b32 s77, v69, 4
	v_readlane_b32 s78, v71, 4
	v_readlane_b32 s79, v73, 4
	v_readlane_b32 s80, v75, 4
	v_mul_f32_e32 v82, s72, v160
	v_fmac_f32_e32 v10, s73, v82
	v_fmac_f32_e32 v11, s74, v82
	v_fmac_f32_e32 v8, s75, v82
	v_fmac_f32_e32 v9, s76, v82
	v_fmac_f32_e32 v6, s77, v82
	v_fmac_f32_e32 v7, s78, v82
	v_fmac_f32_e32 v4, s79, v82
	v_fmac_f32_e32 v5, s80, v82
	v_readlane_b32 s82, v77, 5
	v_readlane_b32 s83, v61, 5
	v_readlane_b32 s84, v63, 5
	v_readlane_b32 s85, v65, 5
	v_readlane_b32 s86, v67, 5
	v_readlane_b32 s87, v69, 5
	v_readlane_b32 s88, v71, 5
	v_readlane_b32 s89, v73, 5
	v_readlane_b32 s90, v75, 5
	v_mul_f32_e32 v83, s82, v161
	v_fmac_f32_e32 v10, s83, v83
	v_fmac_f32_e32 v11, s84, v83
	v_fmac_f32_e32 v8, s85, v83
	v_fmac_f32_e32 v9, s86, v83
	v_fmac_f32_e32 v6, s87, v83
	v_fmac_f32_e32 v7, s88, v83
	v_fmac_f32_e32 v4, s89, v83
	v_fmac_f32_e32 v5, s90, v83
	v_readlane_b32 s72, v77, 6
	v_readlane_b32 s73, v61, 6
	v_readlane_b32 s74, v63, 6
	v_readlane_b32 s75, v65, 6
	v_readlane_b32 s76, v67, 6
	v_readlane_b32 s77, v69, 6
	v_readlane_b32 s78, v71, 6
	v_readlane_b32 s79, v73, 6
	v_readlane_b32 s80, v75, 6
	v_mul_f32_e32 v82, s72, v162
	v_fmac_f32_e32 v10, s73, v82
	v_fmac_f32_e32 v11, s74, v82
	v_fmac_f32_e32 v8, s75, v82
	v_fmac_f32_e32 v9, s76, v82
	v_fmac_f32_e32 v6, s77, v82
	v_fmac_f32_e32 v7, s78, v82
	v_fmac_f32_e32 v4, s79, v82
	v_fmac_f32_e32 v5, s80, v82
	v_readlane_b32 s82, v77, 7
	v_readlane_b32 s83, v61, 7
	v_readlane_b32 s84, v63, 7
	v_readlane_b32 s85, v65, 7
	v_readlane_b32 s86, v67, 7
	v_readlane_b32 s87, v69, 7
	v_readlane_b32 s88, v71, 7
	v_readlane_b32 s89, v73, 7
	v_readlane_b32 s90, v75, 7
	v_mul_f32_e32 v83, s82, v163
	v_fmac_f32_e32 v10, s83, v83
	v_fmac_f32_e32 v11, s84, v83
	v_fmac_f32_e32 v8, s85, v83
	v_fmac_f32_e32 v9, s86, v83
	v_fmac_f32_e32 v6, s87, v83
	v_fmac_f32_e32 v7, s88, v83
	v_fmac_f32_e32 v4, s89, v83
	v_fmac_f32_e32 v5, s90, v83
	global_load_dword v196, v[80:81], off offset:-4096
	global_load_dword v197, v[80:81], off
	v_lshl_add_u64 v[80:81], v[80:81], 0, s[68:69]
	global_load_dword v198, v[80:81], off offset:-4096
	global_load_dword v199, v[80:81], off
	v_lshl_add_u64 v[80:81], v[80:81], 0, s[68:69]
	global_load_dword v200, v[80:81], off offset:-4096
	global_load_dword v201, v[80:81], off
	v_lshl_add_u64 v[80:81], v[80:81], 0, s[68:69]
	global_load_dword v202, v[80:81], off offset:-4096
	global_load_dword v203, v[80:81], off
	v_lshl_add_u64 v[80:81], v[80:81], 0, s[68:69]
	s_waitcnt vmcnt(32)
; __device__ __forceinline__ void prologue(const Params& p, LAS unsigned char* lds) {
;     ...
;             const int l = it >> 10, r = it & 1023, nblk = r & 15, kg = r >> 4, g = kg >> 4, c0 = (kg & 15) * 8, n = nblk * 64 + lane;
;             const float* wp = p.w_pool + ((size_t)l * 4 + g) * 128 * 128 + (size_t)c0 * 128;
;             const float* sc = p.pool_scale + l * 512 + g * 128;
;             const float* wb = p.w_br_pool + (size_t)l * 512 * DM + (size_t)(g * 128) * DM + n;
;             float a[8];
; #pragma unroll
;             for (int i = 0; i < 8; ++i) a[i] = 0.f;
; #pragma unroll 8
;             for (int d = 0; d < 128; ++d) { const float x = wb[(size_t)d * DM] * sc[d];
; #pragma unroll
;                 for (int i = 0; i < 8; ++i) a[i] += wp[i * 128 + d] * x; }
	v_readlane_b32 s72, v77, 8
	v_readlane_b32 s73, v61, 8
	v_readlane_b32 s74, v63, 8
	v_readlane_b32 s75, v65, 8
	v_readlane_b32 s76, v67, 8
	v_readlane_b32 s77, v69, 8
	v_readlane_b32 s78, v71, 8
	v_readlane_b32 s79, v73, 8
	v_readlane_b32 s80, v75, 8
	v_mul_f32_e32 v82, s72, v164
	v_fmac_f32_e32 v10, s73, v82
	v_fmac_f32_e32 v11, s74, v82
	v_fmac_f32_e32 v8, s75, v82
	v_fmac_f32_e32 v9, s76, v82
	v_fmac_f32_e32 v6, s77, v82
	v_fmac_f32_e32 v7, s78, v82
	v_fmac_f32_e32 v4, s79, v82
	v_fmac_f32_e32 v5, s80, v82
	v_readlane_b32 s82, v77, 9
	v_readlane_b32 s83, v61, 9
	v_readlane_b32 s84, v63, 9
	v_readlane_b32 s85, v65, 9
	v_readlane_b32 s86, v67, 9
	v_readlane_b32 s87, v69, 9
	v_readlane_b32 s88, v71, 9
	v_readlane_b32 s89, v73, 9
	v_readlane_b32 s90, v75, 9
	v_mul_f32_e32 v83, s82, v165
	v_fmac_f32_e32 v10, s83, v83
	v_fmac_f32_e32 v11, s84, v83
	v_fmac_f32_e32 v8, s85, v83
	v_fmac_f32_e32 v9, s86, v83
	v_fmac_f32_e32 v6, s87, v83
	v_fmac_f32_e32 v7, s88, v83
	v_fmac_f32_e32 v4, s89, v83
	v_fmac_f32_e32 v5, s90, v83
	v_readlane_b32 s72, v77, 10
	v_readlane_b32 s73, v61, 10
	v_readlane_b32 s74, v63, 10
	v_readlane_b32 s75, v65, 10
	v_readlane_b32 s76, v67, 10
	v_readlane_b32 s77, v69, 10
	v_readlane_b32 s78, v71, 10
	v_readlane_b32 s79, v73, 10
	v_readlane_b32 s80, v75, 10
	v_mul_f32_e32 v82, s72, v166
	v_fmac_f32_e32 v10, s73, v82
	v_fmac_f32_e32 v11, s74, v82
	v_fmac_f32_e32 v8, s75, v82
	v_fmac_f32_e32 v9, s76, v82
	v_fmac_f32_e32 v6, s77, v82
	v_fmac_f32_e32 v7, s78, v82
	v_fmac_f32_e32 v4, s79, v82
	v_fmac_f32_e32 v5, s80, v82
	v_readlane_b32 s82, v77, 11
	v_readlane_b32 s83, v61, 11
	v_readlane_b32 s84, v63, 11
	v_readlane_b32 s85, v65, 11
	v_readlane_b32 s86, v67, 11
	v_readlane_b32 s87, v69, 11
	v_readlane_b32 s88, v71, 11
	v_readlane_b32 s89, v73, 11
	v_readlane_b32 s90, v75, 11
	v_mul_f32_e32 v83, s82, v167
	v_fmac_f32_e32 v10, s83, v83
	v_fmac_f32_e32 v11, s84, v83
	v_fmac_f32_e32 v8, s85, v83
	v_fmac_f32_e32 v9, s86, v83
	v_fmac_f32_e32 v6, s87, v83
	v_fmac_f32_e32 v7, s88, v83
	v_fmac_f32_e32 v4, s89, v83
	v_fmac_f32_e32 v5, s90, v83
	v_readlane_b32 s72, v77, 12
	v_readlane_b32 s73, v61, 12
	v_readlane_b32 s74, v63, 12
	v_readlane_b32 s75, v65, 12
	v_readlane_b32 s76, v67, 12
	v_readlane_b32 s77, v69, 12
	v_readlane_b32 s78, v71, 12
	v_readlane_b32 s79, v73, 12
	v_readlane_b32 s80, v75, 12
	v_mul_f32_e32 v82, s72, v168
	v_fmac_f32_e32 v10, s73, v82
	v_fmac_f32_e32 v11, s74, v82
	v_fmac_f32_e32 v8, s75, v82
	v_fmac_f32_e32 v9, s76, v82
	v_fmac_f32_e32 v6, s77, v82
	v_fmac_f32_e32 v7, s78, v82
	v_fmac_f32_e32 v4, s79, v82
	v_fmac_f32_e32 v5, s80, v82
	v_readlane_b32 s82, v77, 13
	v_readlane_b32 s83, v61, 13
	v_readlane_b32 s84, v63, 13
	v_readlane_b32 s85, v65, 13
	v_readlane_b32 s86, v67, 13
	v_readlane_b32 s87, v69, 13
	v_readlane_b32 s88, v71, 13
	v_readlane_b32 s89, v73, 13
	v_readlane_b32 s90, v75, 13
	v_mul_f32_e32 v83, s82, v169
	v_fmac_f32_e32 v10, s83, v83
	v_fmac_f32_e32 v11, s84, v83
	v_fmac_f32_e32 v8, s85, v83
	v_fmac_f32_e32 v9, s86, v83
	v_fmac_f32_e32 v6, s87, v83
	v_fmac_f32_e32 v7, s88, v83
	v_fmac_f32_e32 v4, s89, v83
	v_fmac_f32_e32 v5, s90, v83
	v_readlane_b32 s72, v77, 14
	v_readlane_b32 s73, v61, 14
	v_readlane_b32 s74, v63, 14
	v_readlane_b32 s75, v65, 14
	v_readlane_b32 s76, v67, 14
	v_readlane_b32 s77, v69, 14
	v_readlane_b32 s78, v71, 14
	v_readlane_b32 s79, v73, 14
	v_readlane_b32 s80, v75, 14
	v_mul_f32_e32 v82, s72, v170
	v_fmac_f32_e32 v10, s73, v82
	v_fmac_f32_e32 v11, s74, v82
	v_fmac_f32_e32 v8, s75, v82
	v_fmac_f32_e32 v9, s76, v82
	v_fmac_f32_e32 v6, s77, v82
	v_fmac_f32_e32 v7, s78, v82
	v_fmac_f32_e32 v4, s79, v82
	v_fmac_f32_e32 v5, s80, v82
	v_readlane_b32 s82, v77, 15
	v_readlane_b32 s83, v61, 15
	v_readlane_b32 s84, v63, 15
	v_readlane_b32 s85, v65, 15
	v_readlane_b32 s86, v67, 15
	v_readlane_b32 s87, v69, 15
	v_readlane_b32 s88, v71, 15
	v_readlane_b32 s89, v73, 15
	v_readlane_b32 s90, v75, 15
	v_mul_f32_e32 v83, s82, v171
	v_fmac_f32_e32 v10, s83, v83
	v_fmac_f32_e32 v11, s84, v83
	v_fmac_f32_e32 v8, s85, v83
	v_fmac_f32_e32 v9, s86, v83
	v_fmac_f32_e32 v6, s87, v83
	v_fmac_f32_e32 v7, s88, v83
	v_fmac_f32_e32 v4, s89, v83
	v_fmac_f32_e32 v5, s90, v83
	global_load_dword v204, v[80:81], off offset:-4096
	global_load_dword v205, v[80:81], off
	v_lshl_add_u64 v[80:81], v[80:81], 0, s[68:69]
	global_load_dword v206, v[80:81], off offset:-4096
	global_load_dword v207, v[80:81], off
	v_lshl_add_u64 v[80:81], v[80:81], 0, s[68:69]
	global_load_dword v208, v[80:81], off offset:-4096
	global_load_dword v209, v[80:81], off
	v_lshl_add_u64 v[80:81], v[80:81], 0, s[68:69]
	global_load_dword v210, v[80:81], off offset:-4096
	global_load_dword v211, v[80:81], off
	v_lshl_add_u64 v[80:81], v[80:81], 0, s[68:69]
	s_waitcnt vmcnt(32)
; __device__ __forceinline__ void prologue(const Params& p, LAS unsigned char* lds) {
;     ...
;             const int l = it >> 10, r = it & 1023, nblk = r & 15, kg = r >> 4, g = kg >> 4, c0 = (kg & 15) * 8, n = nblk * 64 + lane;
;             const float* wp = p.w_pool + ((size_t)l * 4 + g) * 128 * 128 + (size_t)c0 * 128;
;             const float* sc = p.pool_scale + l * 512 + g * 128;
;             const float* wb = p.w_br_pool + (size_t)l * 512 * DM + (size_t)(g * 128) * DM + n;
;             float a[8];
; #pragma unroll
;             for (int i = 0; i < 8; ++i) a[i] = 0.f;
; #pragma unroll 8
;             for (int d = 0; d < 128; ++d) { const float x = wb[(size_t)d * DM] * sc[d];
; #pragma unroll
;                 for (int i = 0; i < 8; ++i) a[i] += wp[i * 128 + d] * x; }
	v_readlane_b32 s72, v77, 16
	v_readlane_b32 s73, v61, 16
	v_readlane_b32 s74, v63, 16
	v_readlane_b32 s75, v65, 16
	v_readlane_b32 s76, v67, 16
	v_readlane_b32 s77, v69, 16
	v_readlane_b32 s78, v71, 16
	v_readlane_b32 s79, v73, 16
	v_readlane_b32 s80, v75, 16
	v_mul_f32_e32 v82, s72, v172
	v_fmac_f32_e32 v10, s73, v82
	v_fmac_f32_e32 v11, s74, v82
	v_fmac_f32_e32 v8, s75, v82
	v_fmac_f32_e32 v9, s76, v82
	v_fmac_f32_e32 v6, s77, v82
	v_fmac_f32_e32 v7, s78, v82
	v_fmac_f32_e32 v4, s79, v82
	v_fmac_f32_e32 v5, s80, v82
	v_readlane_b32 s82, v77, 17
	v_readlane_b32 s83, v61, 17
	v_readlane_b32 s84, v63, 17
	v_readlane_b32 s85, v65, 17
	v_readlane_b32 s86, v67, 17
	v_readlane_b32 s87, v69, 17
	v_readlane_b32 s88, v71, 17
	v_readlane_b32 s89, v73, 17
	v_readlane_b32 s90, v75, 17
	v_mul_f32_e32 v83, s82, v173
	v_fmac_f32_e32 v10, s83, v83
	v_fmac_f32_e32 v11, s84, v83
	v_fmac_f32_e32 v8, s85, v83
	v_fmac_f32_e32 v9, s86, v83
	v_fmac_f32_e32 v6, s87, v83
	v_fmac_f32_e32 v7, s88, v83
	v_fmac_f32_e32 v4, s89, v83
	v_fmac_f32_e32 v5, s90, v83
	v_readlane_b32 s72, v77, 18
	v_readlane_b32 s73, v61, 18
	v_readlane_b32 s74, v63, 18
	v_readlane_b32 s75, v65, 18
	v_readlane_b32 s76, v67, 18
	v_readlane_b32 s77, v69, 18
	v_readlane_b32 s78, v71, 18
	v_readlane_b32 s79, v73, 18
	v_readlane_b32 s80, v75, 18
	v_mul_f32_e32 v82, s72, v174
	v_fmac_f32_e32 v10, s73, v82
	v_fmac_f32_e32 v11, s74, v82
	v_fmac_f32_e32 v8, s75, v82
	v_fmac_f32_e32 v9, s76, v82
	v_fmac_f32_e32 v6, s77, v82
	v_fmac_f32_e32 v7, s78, v82
	v_fmac_f32_e32 v4, s79, v82
	v_fmac_f32_e32 v5, s80, v82
	v_readlane_b32 s82, v77, 19
	v_readlane_b32 s83, v61, 19
	v_readlane_b32 s84, v63, 19
	v_readlane_b32 s85, v65, 19
	v_readlane_b32 s86, v67, 19
	v_readlane_b32 s87, v69, 19
	v_readlane_b32 s88, v71, 19
	v_readlane_b32 s89, v73, 19
	v_readlane_b32 s90, v75, 19
	v_mul_f32_e32 v83, s82, v175
	v_fmac_f32_e32 v10, s83, v83
	v_fmac_f32_e32 v11, s84, v83
	v_fmac_f32_e32 v8, s85, v83
	v_fmac_f32_e32 v9, s86, v83
	v_fmac_f32_e32 v6, s87, v83
	v_fmac_f32_e32 v7, s88, v83
	v_fmac_f32_e32 v4, s89, v83
	v_fmac_f32_e32 v5, s90, v83
	v_readlane_b32 s72, v77, 20
	v_readlane_b32 s73, v61, 20
	v_readlane_b32 s74, v63, 20
	v_readlane_b32 s75, v65, 20
	v_readlane_b32 s76, v67, 20
	v_readlane_b32 s77, v69, 20
	v_readlane_b32 s78, v71, 20
	v_readlane_b32 s79, v73, 20
	v_readlane_b32 s80, v75, 20
	v_mul_f32_e32 v82, s72, v176
	v_fmac_f32_e32 v10, s73, v82
	v_fmac_f32_e32 v11, s74, v82
	v_fmac_f32_e32 v8, s75, v82
	v_fmac_f32_e32 v9, s76, v82
	v_fmac_f32_e32 v6, s77, v82
	v_fmac_f32_e32 v7, s78, v82
	v_fmac_f32_e32 v4, s79, v82
	v_fmac_f32_e32 v5, s80, v82
	v_readlane_b32 s82, v77, 21
	v_readlane_b32 s83, v61, 21
	v_readlane_b32 s84, v63, 21
	v_readlane_b32 s85, v65, 21
	v_readlane_b32 s86, v67, 21
	v_readlane_b32 s87, v69, 21
	v_readlane_b32 s88, v71, 21
	v_readlane_b32 s89, v73, 21
	v_readlane_b32 s90, v75, 21
	v_mul_f32_e32 v83, s82, v177
	v_fmac_f32_e32 v10, s83, v83
	v_fmac_f32_e32 v11, s84, v83
	v_fmac_f32_e32 v8, s85, v83
	v_fmac_f32_e32 v9, s86, v83
	v_fmac_f32_e32 v6, s87, v83
	v_fmac_f32_e32 v7, s88, v83
	v_fmac_f32_e32 v4, s89, v83
	v_fmac_f32_e32 v5, s90, v83
	v_readlane_b32 s72, v77, 22
	v_readlane_b32 s73, v61, 22
	v_readlane_b32 s74, v63, 22
	v_readlane_b32 s75, v65, 22
	v_readlane_b32 s76, v67, 22
	v_readlane_b32 s77, v69, 22
	v_readlane_b32 s78, v71, 22
	v_readlane_b32 s79, v73, 22
	v_readlane_b32 s80, v75, 22
	v_mul_f32_e32 v82, s72, v178
	v_fmac_f32_e32 v10, s73, v82
	v_fmac_f32_e32 v11, s74, v82
	v_fmac_f32_e32 v8, s75, v82
	v_fmac_f32_e32 v9, s76, v82
	v_fmac_f32_e32 v6, s77, v82
	v_fmac_f32_e32 v7, s78, v82
	v_fmac_f32_e32 v4, s79, v82
	v_fmac_f32_e32 v5, s80, v82
	v_readlane_b32 s82, v77, 23
	v_readlane_b32 s83, v61, 23
	v_readlane_b32 s84, v63, 23
	v_readlane_b32 s85, v65, 23
	v_readlane_b32 s86, v67, 23
	v_readlane_b32 s87, v69, 23
	v_readlane_b32 s88, v71, 23
	v_readlane_b32 s89, v73, 23
	v_readlane_b32 s90, v75, 23
	v_mul_f32_e32 v83, s82, v179
	v_fmac_f32_e32 v10, s83, v83
	v_fmac_f32_e32 v11, s84, v83
	v_fmac_f32_e32 v8, s85, v83
	v_fmac_f32_e32 v9, s86, v83
	v_fmac_f32_e32 v6, s87, v83
	v_fmac_f32_e32 v7, s88, v83
	v_fmac_f32_e32 v4, s89, v83
	v_fmac_f32_e32 v5, s90, v83
	global_load_dword v212, v[80:81], off offset:-4096
	global_load_dword v213, v[80:81], off
	v_lshl_add_u64 v[80:81], v[80:81], 0, s[68:69]
	global_load_dword v214, v[80:81], off offset:-4096
	global_load_dword v215, v[80:81], off
	v_lshl_add_u64 v[80:81], v[80:81], 0, s[68:69]
	global_load_dword v216, v[80:81], off offset:-4096
	global_load_dword v217, v[80:81], off
	v_lshl_add_u64 v[80:81], v[80:81], 0, s[68:69]
	global_load_dword v218, v[80:81], off offset:-4096
	global_load_dword v219, v[80:81], off
	v_lshl_add_u64 v[80:81], v[80:81], 0, s[68:69]
	s_waitcnt vmcnt(32)
; __device__ __forceinline__ void prologue(const Params& p, LAS unsigned char* lds) {
;     ...
;             const int l = it >> 10, r = it & 1023, nblk = r & 15, kg = r >> 4, g = kg >> 4, c0 = (kg & 15) * 8, n = nblk * 64 + lane;
;             const float* wp = p.w_pool + ((size_t)l * 4 + g) * 128 * 128 + (size_t)c0 * 128;
;             const float* sc = p.pool_scale + l * 512 + g * 128;
;             const float* wb = p.w_br_pool + (size_t)l * 512 * DM + (size_t)(g * 128) * DM + n;
;             float a[8];
; #pragma unroll
;             for (int i = 0; i < 8; ++i) a[i] = 0.f;
; #pragma unroll 8
;             for (int d = 0; d < 128; ++d) { const float x = wb[(size_t)d * DM] * sc[d];
; #pragma unroll
;                 for (int i = 0; i < 8; ++i) a[i] += wp[i * 128 + d] * x; }
	v_readlane_b32 s72, v77, 24
	v_readlane_b32 s73, v61, 24
	v_readlane_b32 s74, v63, 24
	v_readlane_b32 s75, v65, 24
	v_readlane_b32 s76, v67, 24
	v_readlane_b32 s77, v69, 24
	v_readlane_b32 s78, v71, 24
	v_readlane_b32 s79, v73, 24
	v_readlane_b32 s80, v75, 24
	v_mul_f32_e32 v82, s72, v180
	v_fmac_f32_e32 v10, s73, v82
	v_fmac_f32_e32 v11, s74, v82
	v_fmac_f32_e32 v8, s75, v82
	v_fmac_f32_e32 v9, s76, v82
	v_fmac_f32_e32 v6, s77, v82
	v_fmac_f32_e32 v7, s78, v82
	v_fmac_f32_e32 v4, s79, v82
	v_fmac_f32_e32 v5, s80, v82
	v_readlane_b32 s82, v77, 25
	v_readlane_b32 s83, v61, 25
	v_readlane_b32 s84, v63, 25
	v_readlane_b32 s85, v65, 25
	v_readlane_b32 s86, v67, 25
	v_readlane_b32 s87, v69, 25
	v_readlane_b32 s88, v71, 25
	v_readlane_b32 s89, v73, 25
	v_readlane_b32 s90, v75, 25
	v_mul_f32_e32 v83, s82, v181
	v_fmac_f32_e32 v10, s83, v83
	v_fmac_f32_e32 v11, s84, v83
	v_fmac_f32_e32 v8, s85, v83
	v_fmac_f32_e32 v9, s86, v83
	v_fmac_f32_e32 v6, s87, v83
	v_fmac_f32_e32 v7, s88, v83
	v_fmac_f32_e32 v4, s89, v83
	v_fmac_f32_e32 v5, s90, v83
	v_readlane_b32 s72, v77, 26
	v_readlane_b32 s73, v61, 26
	v_readlane_b32 s74, v63, 26
	v_readlane_b32 s75, v65, 26
	v_readlane_b32 s76, v67, 26
	v_readlane_b32 s77, v69, 26
	v_readlane_b32 s78, v71, 26
	v_readlane_b32 s79, v73, 26
	v_readlane_b32 s80, v75, 26
	v_mul_f32_e32 v82, s72, v182
	v_fmac_f32_e32 v10, s73, v82
	v_fmac_f32_e32 v11, s74, v82
	v_fmac_f32_e32 v8, s75, v82
	v_fmac_f32_e32 v9, s76, v82
	v_fmac_f32_e32 v6, s77, v82
	v_fmac_f32_e32 v7, s78, v82
	v_fmac_f32_e32 v4, s79, v82
	v_fmac_f32_e32 v5, s80, v82
	v_readlane_b32 s82, v77, 27
	v_readlane_b32 s83, v61, 27
	v_readlane_b32 s84, v63, 27
	v_readlane_b32 s85, v65, 27
	v_readlane_b32 s86, v67, 27
	v_readlane_b32 s87, v69, 27
	v_readlane_b32 s88, v71, 27
	v_readlane_b32 s89, v73, 27
	v_readlane_b32 s90, v75, 27
	v_mul_f32_e32 v83, s82, v183
	v_fmac_f32_e32 v10, s83, v83
	v_fmac_f32_e32 v11, s84, v83
	v_fmac_f32_e32 v8, s85, v83
	v_fmac_f32_e32 v9, s86, v83
	v_fmac_f32_e32 v6, s87, v83
	v_fmac_f32_e32 v7, s88, v83
	v_fmac_f32_e32 v4, s89, v83
	v_fmac_f32_e32 v5, s90, v83
	v_readlane_b32 s72, v77, 28
	v_readlane_b32 s73, v61, 28
	v_readlane_b32 s74, v63, 28
	v_readlane_b32 s75, v65, 28
	v_readlane_b32 s76, v67, 28
	v_readlane_b32 s77, v69, 28
	v_readlane_b32 s78, v71, 28
	v_readlane_b32 s79, v73, 28
	v_readlane_b32 s80, v75, 28
	v_mul_f32_e32 v82, s72, v184
	v_fmac_f32_e32 v10, s73, v82
	v_fmac_f32_e32 v11, s74, v82
	v_fmac_f32_e32 v8, s75, v82
	v_fmac_f32_e32 v9, s76, v82
	v_fmac_f32_e32 v6, s77, v82
	v_fmac_f32_e32 v7, s78, v82
	v_fmac_f32_e32 v4, s79, v82
	v_fmac_f32_e32 v5, s80, v82
	v_readlane_b32 s82, v77, 29
	v_readlane_b32 s83, v61, 29
	v_readlane_b32 s84, v63, 29
	v_readlane_b32 s85, v65, 29
	v_readlane_b32 s86, v67, 29
	v_readlane_b32 s87, v69, 29
	v_readlane_b32 s88, v71, 29
	v_readlane_b32 s89, v73, 29
	v_readlane_b32 s90, v75, 29
	v_mul_f32_e32 v83, s82, v185
	v_fmac_f32_e32 v10, s83, v83
	v_fmac_f32_e32 v11, s84, v83
	v_fmac_f32_e32 v8, s85, v83
	v_fmac_f32_e32 v9, s86, v83
	v_fmac_f32_e32 v6, s87, v83
	v_fmac_f32_e32 v7, s88, v83
	v_fmac_f32_e32 v4, s89, v83
	v_fmac_f32_e32 v5, s90, v83
	v_readlane_b32 s72, v77, 30
	v_readlane_b32 s73, v61, 30
	v_readlane_b32 s74, v63, 30
	v_readlane_b32 s75, v65, 30
	v_readlane_b32 s76, v67, 30
	v_readlane_b32 s77, v69, 30
	v_readlane_b32 s78, v71, 30
	v_readlane_b32 s79, v73, 30
	v_readlane_b32 s80, v75, 30
	v_mul_f32_e32 v82, s72, v186
	v_fmac_f32_e32 v10, s73, v82
	v_fmac_f32_e32 v11, s74, v82
	v_fmac_f32_e32 v8, s75, v82
	v_fmac_f32_e32 v9, s76, v82
	v_fmac_f32_e32 v6, s77, v82
	v_fmac_f32_e32 v7, s78, v82
	v_fmac_f32_e32 v4, s79, v82
	v_fmac_f32_e32 v5, s80, v82
	v_readlane_b32 s82, v77, 31
	v_readlane_b32 s83, v61, 31
	v_readlane_b32 s84, v63, 31
	v_readlane_b32 s85, v65, 31
	v_readlane_b32 s86, v67, 31
	v_readlane_b32 s87, v69, 31
	v_readlane_b32 s88, v71, 31
	v_readlane_b32 s89, v73, 31
	v_readlane_b32 s90, v75, 31
	v_mul_f32_e32 v83, s82, v187
	v_fmac_f32_e32 v10, s83, v83
	v_fmac_f32_e32 v11, s84, v83
	v_fmac_f32_e32 v8, s85, v83
	v_fmac_f32_e32 v9, s86, v83
	v_fmac_f32_e32 v6, s87, v83
	v_fmac_f32_e32 v7, s88, v83
	v_fmac_f32_e32 v4, s89, v83
	v_fmac_f32_e32 v5, s90, v83
	s_waitcnt vmcnt(24)
	v_readlane_b32 s72, v77, 32
	v_readlane_b32 s73, v61, 32
	v_readlane_b32 s74, v63, 32
	v_readlane_b32 s75, v65, 32
	v_readlane_b32 s76, v67, 32
	v_readlane_b32 s77, v69, 32
	v_readlane_b32 s78, v71, 32
	v_readlane_b32 s79, v73, 32
	v_readlane_b32 s80, v75, 32
	v_mul_f32_e32 v82, s72, v188
	v_fmac_f32_e32 v10, s73, v82
	v_fmac_f32_e32 v11, s74, v82
	v_fmac_f32_e32 v8, s75, v82
	v_fmac_f32_e32 v9, s76, v82
	v_fmac_f32_e32 v6, s77, v82
	v_fmac_f32_e32 v7, s78, v82
	v_fmac_f32_e32 v4, s79, v82
	v_fmac_f32_e32 v5, s80, v82
	v_readlane_b32 s82, v77, 33
	v_readlane_b32 s83, v61, 33
	v_readlane_b32 s84, v63, 33
	v_readlane_b32 s85, v65, 33
	v_readlane_b32 s86, v67, 33
	v_readlane_b32 s87, v69, 33
	v_readlane_b32 s88, v71, 33
	v_readlane_b32 s89, v73, 33
	v_readlane_b32 s90, v75, 33
	v_mul_f32_e32 v83, s82, v189
	v_fmac_f32_e32 v10, s83, v83
	v_fmac_f32_e32 v11, s84, v83
	v_fmac_f32_e32 v8, s85, v83
	v_fmac_f32_e32 v9, s86, v83
	v_fmac_f32_e32 v6, s87, v83
	v_fmac_f32_e32 v7, s88, v83
	v_fmac_f32_e32 v4, s89, v83
	v_fmac_f32_e32 v5, s90, v83
	v_readlane_b32 s72, v77, 34
	v_readlane_b32 s73, v61, 34
	v_readlane_b32 s74, v63, 34
	v_readlane_b32 s75, v65, 34
	v_readlane_b32 s76, v67, 34
	v_readlane_b32 s77, v69, 34
	v_readlane_b32 s78, v71, 34
	v_readlane_b32 s79, v73, 34
	v_readlane_b32 s80, v75, 34
	v_mul_f32_e32 v82, s72, v190
	v_fmac_f32_e32 v10, s73, v82
	v_fmac_f32_e32 v11, s74, v82
	v_fmac_f32_e32 v8, s75, v82
; __device__ __forceinline__ void prologue(const Params& p, LAS unsigned char* lds) {
;     ...
;             const int l = it >> 10, r = it & 1023, nblk = r & 15, kg = r >> 4, g = kg >> 4, c0 = (kg & 15) * 8, n = nblk * 64 + lane;
;             const float* wp = p.w_pool + ((size_t)l * 4 + g) * 128 * 128 + (size_t)c0 * 128;
;             const float* sc = p.pool_scale + l * 512 + g * 128;
;             const float* wb = p.w_br_pool + (size_t)l * 512 * DM + (size_t)(g * 128) * DM + n;
;             float a[8];
; #pragma unroll
;             for (int i = 0; i < 8; ++i) a[i] = 0.f;
; #pragma unroll 8
;             for (int d = 0; d < 128; ++d) { const float x = wb[(size_t)d * DM] * sc[d];
; #pragma unroll
;                 for (int i = 0; i < 8; ++i) a[i] += wp[i * 128 + d] * x; }
	v_fmac_f32_e32 v9, s76, v82
	v_fmac_f32_e32 v6, s77, v82
	v_fmac_f32_e32 v7, s78, v82
	v_fmac_f32_e32 v4, s79, v82
	v_fmac_f32_e32 v5, s80, v82
	v_readlane_b32 s82, v77, 35
	v_readlane_b32 s83, v61, 35
	v_readlane_b32 s84, v63, 35
	v_readlane_b32 s85, v65, 35
	v_readlane_b32 s86, v67, 35
	v_readlane_b32 s87, v69, 35
	v_readlane_b32 s88, v71, 35
	v_readlane_b32 s89, v73, 35
	v_readlane_b32 s90, v75, 35
	v_mul_f32_e32 v83, s82, v191
	v_fmac_f32_e32 v10, s83, v83
	v_fmac_f32_e32 v11, s84, v83
	v_fmac_f32_e32 v8, s85, v83
	v_fmac_f32_e32 v9, s86, v83
	v_fmac_f32_e32 v6, s87, v83
	v_fmac_f32_e32 v7, s88, v83
	v_fmac_f32_e32 v4, s89, v83
	v_fmac_f32_e32 v5, s90, v83
	v_readlane_b32 s72, v77, 36
	v_readlane_b32 s73, v61, 36
	v_readlane_b32 s74, v63, 36
	v_readlane_b32 s75, v65, 36
	v_readlane_b32 s76, v67, 36
	v_readlane_b32 s77, v69, 36
	v_readlane_b32 s78, v71, 36
	v_readlane_b32 s79, v73, 36
	v_readlane_b32 s80, v75, 36
	v_mul_f32_e32 v82, s72, v192
	v_fmac_f32_e32 v10, s73, v82
	v_fmac_f32_e32 v11, s74, v82
	v_fmac_f32_e32 v8, s75, v82
	v_fmac_f32_e32 v9, s76, v82
	v_fmac_f32_e32 v6, s77, v82
	v_fmac_f32_e32 v7, s78, v82
	v_fmac_f32_e32 v4, s79, v82
	v_fmac_f32_e32 v5, s80, v82
	v_readlane_b32 s82, v77, 37
	v_readlane_b32 s83, v61, 37
	v_readlane_b32 s84, v63, 37
	v_readlane_b32 s85, v65, 37
	v_readlane_b32 s86, v67, 37
	v_readlane_b32 s87, v69, 37
	v_readlane_b32 s88, v71, 37
	v_readlane_b32 s89, v73, 37
	v_readlane_b32 s90, v75, 37
	v_mul_f32_e32 v83, s82, v193
	v_fmac_f32_e32 v10, s83, v83
	v_fmac_f32_e32 v11, s84, v83
	v_fmac_f32_e32 v8, s85, v83
	v_fmac_f32_e32 v9, s86, v83
	v_fmac_f32_e32 v6, s87, v83
	v_fmac_f32_e32 v7, s88, v83
	v_fmac_f32_e32 v4, s89, v83
	v_fmac_f32_e32 v5, s90, v83
	v_readlane_b32 s72, v77, 38
	v_readlane_b32 s73, v61, 38
	v_readlane_b32 s74, v63, 38
	v_readlane_b32 s75, v65, 38
	v_readlane_b32 s76, v67, 38
	v_readlane_b32 s77, v69, 38
	v_readlane_b32 s78, v71, 38
	v_readlane_b32 s79, v73, 38
	v_readlane_b32 s80, v75, 38
	v_mul_f32_e32 v82, s72, v194
	v_fmac_f32_e32 v10, s73, v82
	v_fmac_f32_e32 v11, s74, v82
	v_fmac_f32_e32 v8, s75, v82
	v_fmac_f32_e32 v9, s76, v82
	v_fmac_f32_e32 v6, s77, v82
	v_fmac_f32_e32 v7, s78, v82
	v_fmac_f32_e32 v4, s79, v82
	v_fmac_f32_e32 v5, s80, v82
	v_readlane_b32 s82, v77, 39
	v_readlane_b32 s83, v61, 39
	v_readlane_b32 s84, v63, 39
	v_readlane_b32 s85, v65, 39
	v_readlane_b32 s86, v67, 39
	v_readlane_b32 s87, v69, 39
	v_readlane_b32 s88, v71, 39
	v_readlane_b32 s89, v73, 39
	v_readlane_b32 s90, v75, 39
	v_mul_f32_e32 v83, s82, v195
	v_fmac_f32_e32 v10, s83, v83
	v_fmac_f32_e32 v11, s84, v83
	v_fmac_f32_e32 v8, s85, v83
	v_fmac_f32_e32 v9, s86, v83
	v_fmac_f32_e32 v6, s87, v83
	v_fmac_f32_e32 v7, s88, v83
	v_fmac_f32_e32 v4, s89, v83
	v_fmac_f32_e32 v5, s90, v83
	s_waitcnt vmcnt(16)
	v_readlane_b32 s72, v77, 40
	v_readlane_b32 s73, v61, 40
	v_readlane_b32 s74, v63, 40
	v_readlane_b32 s75, v65, 40
	v_readlane_b32 s76, v67, 40
	v_readlane_b32 s77, v69, 40
	v_readlane_b32 s78, v71, 40
	v_readlane_b32 s79, v73, 40
	v_readlane_b32 s80, v75, 40
	v_mul_f32_e32 v82, s72, v196
	v_fmac_f32_e32 v10, s73, v82
	v_fmac_f32_e32 v11, s74, v82
	v_fmac_f32_e32 v8, s75, v82
	v_fmac_f32_e32 v9, s76, v82
	v_fmac_f32_e32 v6, s77, v82
	v_fmac_f32_e32 v7, s78, v82
	v_fmac_f32_e32 v4, s79, v82
	v_fmac_f32_e32 v5, s80, v82
	v_readlane_b32 s82, v77, 41
	v_readlane_b32 s83, v61, 41
	v_readlane_b32 s84, v63, 41
	v_readlane_b32 s85, v65, 41
	v_readlane_b32 s86, v67, 41
	v_readlane_b32 s87, v69, 41
	v_readlane_b32 s88, v71, 41
	v_readlane_b32 s89, v73, 41
	v_readlane_b32 s90, v75, 41
	v_mul_f32_e32 v83, s82, v197
	v_fmac_f32_e32 v10, s83, v83
	v_fmac_f32_e32 v11, s84, v83
	v_fmac_f32_e32 v8, s85, v83
	v_fmac_f32_e32 v9, s86, v83
	v_fmac_f32_e32 v6, s87, v83
	v_fmac_f32_e32 v7, s88, v83
	v_fmac_f32_e32 v4, s89, v83
	v_fmac_f32_e32 v5, s90, v83
	v_readlane_b32 s72, v77, 42
	v_readlane_b32 s73, v61, 42
	v_readlane_b32 s74, v63, 42
	v_readlane_b32 s75, v65, 42
	v_readlane_b32 s76, v67, 42
	v_readlane_b32 s77, v69, 42
	v_readlane_b32 s78, v71, 42
	v_readlane_b32 s79, v73, 42
	v_readlane_b32 s80, v75, 42
	v_mul_f32_e32 v82, s72, v198
	v_fmac_f32_e32 v10, s73, v82
	v_fmac_f32_e32 v11, s74, v82
	v_fmac_f32_e32 v8, s75, v82
	v_fmac_f32_e32 v9, s76, v82
	v_fmac_f32_e32 v6, s77, v82
	v_fmac_f32_e32 v7, s78, v82
	v_fmac_f32_e32 v4, s79, v82
	v_fmac_f32_e32 v5, s80, v82
	v_readlane_b32 s82, v77, 43
	v_readlane_b32 s83, v61, 43
	v_readlane_b32 s84, v63, 43
	v_readlane_b32 s85, v65, 43
	v_readlane_b32 s86, v67, 43
	v_readlane_b32 s87, v69, 43
	v_readlane_b32 s88, v71, 43
	v_readlane_b32 s89, v73, 43
	v_readlane_b32 s90, v75, 43
	v_mul_f32_e32 v83, s82, v199
	v_fmac_f32_e32 v10, s83, v83
	v_fmac_f32_e32 v11, s84, v83
	v_fmac_f32_e32 v8, s85, v83
	v_fmac_f32_e32 v9, s86, v83
	v_fmac_f32_e32 v6, s87, v83
	v_fmac_f32_e32 v7, s88, v83
	v_fmac_f32_e32 v4, s89, v83
	v_fmac_f32_e32 v5, s90, v83
	v_readlane_b32 s72, v77, 44
	v_readlane_b32 s73, v61, 44
	v_readlane_b32 s74, v63, 44
	v_readlane_b32 s75, v65, 44
	v_readlane_b32 s76, v67, 44
	v_readlane_b32 s77, v69, 44
	v_readlane_b32 s78, v71, 44
	v_readlane_b32 s79, v73, 44
	v_readlane_b32 s80, v75, 44
	v_mul_f32_e32 v82, s72, v200
	v_fmac_f32_e32 v10, s73, v82
	v_fmac_f32_e32 v11, s74, v82
	v_fmac_f32_e32 v8, s75, v82
	v_fmac_f32_e32 v9, s76, v82
	v_fmac_f32_e32 v6, s77, v82
	v_fmac_f32_e32 v7, s78, v82
	v_fmac_f32_e32 v4, s79, v82
	v_fmac_f32_e32 v5, s80, v82
	v_readlane_b32 s82, v77, 45
	v_readlane_b32 s83, v61, 45
	v_readlane_b32 s84, v63, 45
	v_readlane_b32 s85, v65, 45
	v_readlane_b32 s86, v67, 45
	v_readlane_b32 s87, v69, 45
	v_readlane_b32 s88, v71, 45
	v_readlane_b32 s89, v73, 45
	v_readlane_b32 s90, v75, 45
	v_mul_f32_e32 v83, s82, v201
	v_fmac_f32_e32 v10, s83, v83
	v_fmac_f32_e32 v11, s84, v83
	v_fmac_f32_e32 v8, s85, v83
	v_fmac_f32_e32 v9, s86, v83
	v_fmac_f32_e32 v6, s87, v83
	v_fmac_f32_e32 v7, s88, v83
	v_fmac_f32_e32 v4, s89, v83
	v_fmac_f32_e32 v5, s90, v83
	v_readlane_b32 s72, v77, 46
	v_readlane_b32 s73, v61, 46
	v_readlane_b32 s74, v63, 46
	v_readlane_b32 s75, v65, 46
	v_readlane_b32 s76, v67, 46
	v_readlane_b32 s77, v69, 46
	v_readlane_b32 s78, v71, 46
	v_readlane_b32 s79, v73, 46
	v_readlane_b32 s80, v75, 46
	v_mul_f32_e32 v82, s72, v202
	v_fmac_f32_e32 v10, s73, v82
	v_fmac_f32_e32 v11, s74, v82
	v_fmac_f32_e32 v8, s75, v82
	v_fmac_f32_e32 v9, s76, v82
	v_fmac_f32_e32 v6, s77, v82
	v_fmac_f32_e32 v7, s78, v82
	v_fmac_f32_e32 v4, s79, v82
	v_fmac_f32_e32 v5, s80, v82
	v_readlane_b32 s82, v77, 47
	v_readlane_b32 s83, v61, 47
	v_readlane_b32 s84, v63, 47
	v_readlane_b32 s85, v65, 47
	v_readlane_b32 s86, v67, 47
	v_readlane_b32 s87, v69, 47
	v_readlane_b32 s88, v71, 47
	v_readlane_b32 s89, v73, 47
	v_readlane_b32 s90, v75, 47
	v_mul_f32_e32 v83, s82, v203
	v_fmac_f32_e32 v10, s83, v83
	v_fmac_f32_e32 v11, s84, v83
	v_fmac_f32_e32 v8, s85, v83
	v_fmac_f32_e32 v9, s86, v83
	v_fmac_f32_e32 v6, s87, v83
	v_fmac_f32_e32 v7, s88, v83
	v_fmac_f32_e32 v4, s89, v83
	v_fmac_f32_e32 v5, s90, v83
	s_waitcnt vmcnt(8)
; __device__ __forceinline__ void prologue(const Params& p, LAS unsigned char* lds) {
;     ...
; #pragma unroll 8
;             for (int d = 0; d < 128; ++d) { const float x = wb[(size_t)d * DM] * sc[d];
; #pragma unroll
;                 for (int i = 0; i < 8; ++i) a[i] += wp[i * 128 + d] * x; }
	v_readlane_b32 s72, v77, 48
	v_readlane_b32 s73, v61, 48
	v_readlane_b32 s74, v63, 48
	v_readlane_b32 s75, v65, 48
	v_readlane_b32 s76, v67, 48
	v_readlane_b32 s77, v69, 48
	v_readlane_b32 s78, v71, 48
	v_readlane_b32 s79, v73, 48
	v_readlane_b32 s80, v75, 48
	v_mul_f32_e32 v82, s72, v204
	v_fmac_f32_e32 v10, s73, v82
	v_fmac_f32_e32 v11, s74, v82
	v_fmac_f32_e32 v8, s75, v82
	v_fmac_f32_e32 v9, s76, v82
	v_fmac_f32_e32 v6, s77, v82
	v_fmac_f32_e32 v7, s78, v82
	v_fmac_f32_e32 v4, s79, v82
	v_fmac_f32_e32 v5, s80, v82
	v_readlane_b32 s82, v77, 49
	v_readlane_b32 s83, v61, 49
	v_readlane_b32 s84, v63, 49
	v_readlane_b32 s85, v65, 49
	v_readlane_b32 s86, v67, 49
	v_readlane_b32 s87, v69, 49
	v_readlane_b32 s88, v71, 49
	v_readlane_b32 s89, v73, 49
	v_readlane_b32 s90, v75, 49
	v_mul_f32_e32 v83, s82, v205
	v_fmac_f32_e32 v10, s83, v83
	v_fmac_f32_e32 v11, s84, v83
	v_fmac_f32_e32 v8, s85, v83
	v_fmac_f32_e32 v9, s86, v83
	v_fmac_f32_e32 v6, s87, v83
	v_fmac_f32_e32 v7, s88, v83
	v_fmac_f32_e32 v4, s89, v83
	v_fmac_f32_e32 v5, s90, v83
	v_readlane_b32 s72, v77, 50
	v_readlane_b32 s73, v61, 50
	v_readlane_b32 s74, v63, 50
	v_readlane_b32 s75, v65, 50
	v_readlane_b32 s76, v67, 50
	v_readlane_b32 s77, v69, 50
	v_readlane_b32 s78, v71, 50
	v_readlane_b32 s79, v73, 50
	v_readlane_b32 s80, v75, 50
	v_mul_f32_e32 v82, s72, v206
	v_fmac_f32_e32 v10, s73, v82
	v_fmac_f32_e32 v11, s74, v82
	v_fmac_f32_e32 v8, s75, v82
	v_fmac_f32_e32 v9, s76, v82
	v_fmac_f32_e32 v6, s77, v82
	v_fmac_f32_e32 v7, s78, v82
	v_fmac_f32_e32 v4, s79, v82
	v_fmac_f32_e32 v5, s80, v82
	v_readlane_b32 s82, v77, 51
	v_readlane_b32 s83, v61, 51
	v_readlane_b32 s84, v63, 51
	v_readlane_b32 s85, v65, 51
	v_readlane_b32 s86, v67, 51
	v_readlane_b32 s87, v69, 51
	v_readlane_b32 s88, v71, 51
	v_readlane_b32 s89, v73, 51
	v_readlane_b32 s90, v75, 51
	v_mul_f32_e32 v83, s82, v207
	v_fmac_f32_e32 v10, s83, v83
	v_fmac_f32_e32 v11, s84, v83
	v_fmac_f32_e32 v8, s85, v83
	v_fmac_f32_e32 v9, s86, v83
	v_fmac_f32_e32 v6, s87, v83
	v_fmac_f32_e32 v7, s88, v83
	v_fmac_f32_e32 v4, s89, v83
	v_fmac_f32_e32 v5, s90, v83
	v_readlane_b32 s72, v77, 52
	v_readlane_b32 s73, v61, 52
	v_readlane_b32 s74, v63, 52
	v_readlane_b32 s75, v65, 52
	v_readlane_b32 s76, v67, 52
	v_readlane_b32 s77, v69, 52
	v_readlane_b32 s78, v71, 52
	v_readlane_b32 s79, v73, 52
	v_readlane_b32 s80, v75, 52
	v_mul_f32_e32 v82, s72, v208
	v_fmac_f32_e32 v10, s73, v82
	v_fmac_f32_e32 v11, s74, v82
	v_fmac_f32_e32 v8, s75, v82
	v_fmac_f32_e32 v9, s76, v82
	v_fmac_f32_e32 v6, s77, v82
	v_fmac_f32_e32 v7, s78, v82
	v_fmac_f32_e32 v4, s79, v82
	v_fmac_f32_e32 v5, s80, v82
	v_readlane_b32 s82, v77, 53
	v_readlane_b32 s83, v61, 53
	v_readlane_b32 s84, v63, 53
	v_readlane_b32 s85, v65, 53
	v_readlane_b32 s86, v67, 53
	v_readlane_b32 s87, v69, 53
	v_readlane_b32 s88, v71, 53
	v_readlane_b32 s89, v73, 53
	v_readlane_b32 s90, v75, 53
	v_mul_f32_e32 v83, s82, v209
	v_fmac_f32_e32 v10, s83, v83
	v_fmac_f32_e32 v11, s84, v83
	v_fmac_f32_e32 v8, s85, v83
	v_fmac_f32_e32 v9, s86, v83
	v_fmac_f32_e32 v6, s87, v83
	v_fmac_f32_e32 v7, s88, v83
	v_fmac_f32_e32 v4, s89, v83
	v_fmac_f32_e32 v5, s90, v83
	v_readlane_b32 s72, v77, 54
	v_readlane_b32 s73, v61, 54
	v_readlane_b32 s74, v63, 54
	v_readlane_b32 s75, v65, 54
	v_readlane_b32 s76, v67, 54
	v_readlane_b32 s77, v69, 54
	v_readlane_b32 s78, v71, 54
	v_readlane_b32 s79, v73, 54
	v_readlane_b32 s80, v75, 54
	v_mul_f32_e32 v82, s72, v210
	v_fmac_f32_e32 v10, s73, v82
	v_fmac_f32_e32 v11, s74, v82
	v_fmac_f32_e32 v8, s75, v82
	v_fmac_f32_e32 v9, s76, v82
	v_fmac_f32_e32 v6, s77, v82
	v_fmac_f32_e32 v7, s78, v82
	v_fmac_f32_e32 v4, s79, v82
	v_fmac_f32_e32 v5, s80, v82
	v_readlane_b32 s82, v77, 55
	v_readlane_b32 s83, v61, 55
	v_readlane_b32 s84, v63, 55
	v_readlane_b32 s85, v65, 55
	v_readlane_b32 s86, v67, 55
	v_readlane_b32 s87, v69, 55
	v_readlane_b32 s88, v71, 55
	v_readlane_b32 s89, v73, 55
	v_readlane_b32 s90, v75, 55
	v_mul_f32_e32 v83, s82, v211
	v_fmac_f32_e32 v10, s83, v83
	v_fmac_f32_e32 v11, s84, v83
	v_fmac_f32_e32 v8, s85, v83
	v_fmac_f32_e32 v9, s86, v83
	v_fmac_f32_e32 v6, s87, v83
	v_fmac_f32_e32 v7, s88, v83
	v_fmac_f32_e32 v4, s89, v83
	v_fmac_f32_e32 v5, s90, v83
	s_waitcnt vmcnt(0)
; __device__ __forceinline__ u32x4 pack8(const float* f) { u32x4 w; w.x = cvt_pk_bf16(f[0], f[1]); w.y = cvt_pk_bf16(f[2], f[3]); w.z = cvt_pk_bf16(f[4], f[5]); w.w = cvt_pk_bf16(f[6], f[7]); return w; }
; __device__ __forceinline__ void prologue(const Params& p, LAS unsigned char* lds) {
;     ...
; #pragma unroll 8
;             for (int d = 0; d < 128; ++d) { const float x = wb[(size_t)d * DM] * sc[d];
; #pragma unroll
;                 for (int i = 0; i < 8; ++i) a[i] += wp[i * 128 + d] * x; }
;             bf16_t* dst = (bf16_t*)(p.ws + WS_W + (size_t)l * W_LAYER + WO_MIX) + (size_t)(1024 + n) * 512 + g * 128 + c0;
;             *(u32x4*)dst = pack8(a);
	v_readlane_b32 s72, v77, 56
	v_readlane_b32 s73, v61, 56
	v_readlane_b32 s74, v63, 56
	v_readlane_b32 s75, v65, 56
	v_readlane_b32 s76, v67, 56
	v_readlane_b32 s77, v69, 56
	v_readlane_b32 s78, v71, 56
	v_readlane_b32 s79, v73, 56
	v_readlane_b32 s80, v75, 56
	v_mul_f32_e32 v82, s72, v212
	v_fmac_f32_e32 v10, s73, v82
	v_fmac_f32_e32 v11, s74, v82
	v_fmac_f32_e32 v8, s75, v82
	v_fmac_f32_e32 v9, s76, v82
	v_fmac_f32_e32 v6, s77, v82
	v_fmac_f32_e32 v7, s78, v82
	v_fmac_f32_e32 v4, s79, v82
	v_fmac_f32_e32 v5, s80, v82
	v_readlane_b32 s82, v77, 57
	v_readlane_b32 s83, v61, 57
	v_readlane_b32 s84, v63, 57
	v_readlane_b32 s85, v65, 57
	v_readlane_b32 s86, v67, 57
	v_readlane_b32 s87, v69, 57
	v_readlane_b32 s88, v71, 57
	v_readlane_b32 s89, v73, 57
	v_readlane_b32 s90, v75, 57
	v_mul_f32_e32 v83, s82, v213
	v_fmac_f32_e32 v10, s83, v83
	v_fmac_f32_e32 v11, s84, v83
	v_fmac_f32_e32 v8, s85, v83
	v_fmac_f32_e32 v9, s86, v83
	v_fmac_f32_e32 v6, s87, v83
	v_fmac_f32_e32 v7, s88, v83
	v_fmac_f32_e32 v4, s89, v83
	v_fmac_f32_e32 v5, s90, v83
	v_readlane_b32 s72, v77, 58
	v_readlane_b32 s73, v61, 58
	v_readlane_b32 s74, v63, 58
	v_readlane_b32 s75, v65, 58
	v_readlane_b32 s76, v67, 58
	v_readlane_b32 s77, v69, 58
	v_readlane_b32 s78, v71, 58
	v_readlane_b32 s79, v73, 58
	v_readlane_b32 s80, v75, 58
	v_mul_f32_e32 v82, s72, v214
	v_fmac_f32_e32 v10, s73, v82
	v_fmac_f32_e32 v11, s74, v82
	v_fmac_f32_e32 v8, s75, v82
	v_fmac_f32_e32 v9, s76, v82
	v_fmac_f32_e32 v6, s77, v82
	v_fmac_f32_e32 v7, s78, v82
	v_fmac_f32_e32 v4, s79, v82
	v_fmac_f32_e32 v5, s80, v82
	v_readlane_b32 s82, v77, 59
	v_readlane_b32 s83, v61, 59
	v_readlane_b32 s84, v63, 59
	v_readlane_b32 s85, v65, 59
	v_readlane_b32 s86, v67, 59
	v_readlane_b32 s87, v69, 59
	v_readlane_b32 s88, v71, 59
	v_readlane_b32 s89, v73, 59
	v_readlane_b32 s90, v75, 59
	v_mul_f32_e32 v83, s82, v215
	v_fmac_f32_e32 v10, s83, v83
	v_fmac_f32_e32 v11, s84, v83
	v_fmac_f32_e32 v8, s85, v83
	v_fmac_f32_e32 v9, s86, v83
	v_fmac_f32_e32 v6, s87, v83
	v_fmac_f32_e32 v7, s88, v83
	v_fmac_f32_e32 v4, s89, v83
	v_fmac_f32_e32 v5, s90, v83
	v_readlane_b32 s72, v77, 60
	v_readlane_b32 s73, v61, 60
	v_readlane_b32 s74, v63, 60
	v_readlane_b32 s75, v65, 60
	v_readlane_b32 s76, v67, 60
	v_readlane_b32 s77, v69, 60
	v_readlane_b32 s78, v71, 60
	v_readlane_b32 s79, v73, 60
	v_readlane_b32 s80, v75, 60
	v_mul_f32_e32 v82, s72, v216
	v_fmac_f32_e32 v10, s73, v82
	v_fmac_f32_e32 v11, s74, v82
	v_fmac_f32_e32 v8, s75, v82
	v_fmac_f32_e32 v9, s76, v82
	v_fmac_f32_e32 v6, s77, v82
	v_fmac_f32_e32 v7, s78, v82
	v_fmac_f32_e32 v4, s79, v82
	v_fmac_f32_e32 v5, s80, v82
	v_readlane_b32 s82, v77, 61
	v_readlane_b32 s83, v61, 61
	v_readlane_b32 s84, v63, 61
	v_readlane_b32 s85, v65, 61
	v_readlane_b32 s86, v67, 61
	v_readlane_b32 s87, v69, 61
	v_readlane_b32 s88, v71, 61
	v_readlane_b32 s89, v73, 61
	v_readlane_b32 s90, v75, 61
	v_mul_f32_e32 v83, s82, v217
	v_fmac_f32_e32 v10, s83, v83
	v_fmac_f32_e32 v11, s84, v83
	v_fmac_f32_e32 v8, s85, v83
	v_fmac_f32_e32 v9, s86, v83
	v_fmac_f32_e32 v6, s87, v83
	v_fmac_f32_e32 v7, s88, v83
	v_fmac_f32_e32 v4, s89, v83
	v_fmac_f32_e32 v5, s90, v83
	v_readlane_b32 s72, v77, 62
	v_readlane_b32 s73, v61, 62
	v_readlane_b32 s74, v63, 62
	v_readlane_b32 s75, v65, 62
	v_readlane_b32 s76, v67, 62
	v_readlane_b32 s77, v69, 62
	v_readlane_b32 s78, v71, 62
	v_readlane_b32 s79, v73, 62
	v_readlane_b32 s80, v75, 62
	v_mul_f32_e32 v82, s72, v218
	v_fmac_f32_e32 v10, s73, v82
	v_fmac_f32_e32 v11, s74, v82
	v_fmac_f32_e32 v8, s75, v82
	v_fmac_f32_e32 v9, s76, v82
	v_fmac_f32_e32 v6, s77, v82
	v_fmac_f32_e32 v7, s78, v82
	v_fmac_f32_e32 v4, s79, v82
	v_fmac_f32_e32 v5, s80, v82
	v_readlane_b32 s82, v77, 63
	v_readlane_b32 s83, v61, 63
	v_readlane_b32 s84, v63, 63
	v_readlane_b32 s85, v65, 63
	v_readlane_b32 s86, v67, 63
	v_readlane_b32 s87, v69, 63
	v_readlane_b32 s88, v71, 63
	v_readlane_b32 s89, v73, 63
	v_readlane_b32 s90, v75, 63
	v_mul_f32_e32 v83, s82, v219
	v_fmac_f32_e32 v10, s83, v83
	v_fmac_f32_e32 v11, s84, v83
	v_fmac_f32_e32 v8, s85, v83
	v_fmac_f32_e32 v9, s86, v83
	v_fmac_f32_e32 v6, s87, v83
	v_fmac_f32_e32 v7, s88, v83
	v_fmac_f32_e32 v4, s89, v83
	v_fmac_f32_e32 v5, s90, v83
	s_lshl_b32 s11, s24, 6
	s_and_b32 s11, s11, 0x3c0
	s_and_b32 s4, s4, 3
	v_or_b32_e32 v0, s11, v39
	s_mul_hi_i32 s11, s10, 0x1b00000
	s_mul_i32 s10, s10, 0x1b00000
	s_add_u32 s10, s50, s10
	s_addc_u32 s11, s51, s11
	v_lshlrev_b32_e32 v0, 10, v0
	v_lshl_add_u64 v[2:3], s[10:11], 0, v[0:1]
	s_lshl_b32 s4, s4, 8
	v_lshl_add_u64 v[2:3], v[2:3], 0, s[4:5]
	s_and_b32 s4, s24, 0xf0
	v_lshl_add_u64 v[2:3], v[2:3], 0, s[4:5]
	v_add_co_u32_e32 v2, vcc, 0x880000, v2
	s_add_i32 s24, s24, s32
	s_add_i32 s1, s1, s33
	v_addc_co_u32_e32 v3, vcc, 0, v3, vcc
	s_cmpk_gt_i32 s24, 0x7ff
	v_cvt_pk_bf16_f32 v10, v10, v11
	v_cvt_pk_bf16_f32 v11, v8, v9
	v_cvt_pk_bf16_f32 v12, v6, v7
	v_cvt_pk_bf16_f32 v13, v4, v5
	global_store_dwordx4 v[2:3], v[10:13], off
	s_cbranch_scc0 .LBB0_48

; __device__ __forceinline__ void prologue(const Params& p, LAS unsigned char* lds) {
;     ...
;     {
;         bf16_t* XB = (bf16_t*)(p.ws + WS_XB);
;         const int gw = blockIdx.x * 8 + wid, NGW = gridDim.x * 8;
; #pragma unroll 1
;         for (int m0 = gw; m0 < MREAL; m0 += 4 * NGW) {
;             f32x4 v[4][4];
; #pragma unroll
;             for (int r = 0; r < 4; ++r) { const int m = m0 + r * NGW;
;                 if (m < MREAL) { const f32x4* xr = (const f32x4*)(m < MP ? p.xp + (size_t)m * DM : p.xs + (size_t)(m - MP) * DM) + lane;
.LBB0_65:
	v_readfirstlane_b32 s32, v222
	v_mbcnt_lo_u32_b32 v68, -1, 0
	s_lshr_b32 s32, s32, 6
	s_cmp_gt_u32 s32, 5
	s_cbranch_scc1 .LBB0_88
	s_mul_i32 s0, s81, 6
	s_add_i32 s0, s0, s32
	s_mul_i32 s6, s92, 6
	s_cmp_gt_i32 s0, 0x807f
	s_cbranch_scc1 .LBB0_88
	v_lshlrev_b32_e32 v64, 3, v39
	v_mov_b32_e32 v65, 0
	v_lshl_add_u64 v[0:1], s[50:51], 0, v[64:65]
	s_mov_b64 s[4:5], 0x3800000
	v_lshl_add_u64 v[66:67], v[0:1], 0, s[4:5]
	v_cmp_eq_u32_e64 s[4:5], 0, v39
	s_mul_i32 s23, s92, 12
	s_mul_i32 s24, s92, 18
	v_lshlrev_b32_e32 v64, 4, v39
	v_mbcnt_hi_u32_b32 v69, -1, v68
	s_branch .LBB0_69
